# scan-phase wave priority: s_setprio 3 around the pipelined mLSTM scan loop of the scan workgroups, back to 0 afterwards
# baseline (speedup 1.0000x reference)
.Lscan_entry:
	s_setprio 3
	s_mov_b32 s2, 0xfe03f81
	s_mov_b32 s18, 0xcd0000
	s_mov_b64 s[16:17], 0x40800
	s_mov_b32 s19, s76

.LBB0_484:
	v_add_u32_e32 v0, 0xdcd1000, v0
	v_add_u32_e32 v2, 0xcd0000, v2
	s_mov_b64 s[100:101], s[58:59]
	s_mov_b64 s[98:99], s[58:59]
	global_load_dwordx4 v[44:47], v0, s[100:101]
	s_add_u32 s100, s100, 0x8100
	s_addc_u32 s101, s101, 0
	global_load_dwordx4 v[48:51], v0, s[100:101]
	s_add_u32 s100, s100, 0x8100
	s_addc_u32 s101, s101, 0
	global_load_dwordx4 v[52:55], v0, s[100:101]
	s_add_u32 s100, s100, 0x8100
	s_addc_u32 s101, s101, 0
	global_load_dwordx4 v[56:59], v0, s[100:101]
	s_add_u32 s100, s100, 0x8100
	s_addc_u32 s101, s101, 0
	global_load_dwordx4 v[60:63], v0, s[100:101]
	s_add_u32 s100, s100, 0x8100
	s_addc_u32 s101, s101, 0
	global_load_dwordx4 v[64:67], v0, s[100:101]
	s_add_u32 s100, s100, 0x8100
	s_addc_u32 s101, s101, 0
	global_load_dwordx4 v[68:71], v0, s[100:101]
	s_add_u32 s100, s100, 0x8100
	s_addc_u32 s101, s101, 0
	global_load_dwordx4 v[72:75], v0, s[100:101]
	s_add_u32 s100, s100, 0x8100
	s_addc_u32 s101, s101, 0
	global_load_dword v108, v2, s[58:59]
	global_load_dword v109, v2, s[58:59] offset:4
	global_load_dword v110, v2, s[58:59] offset:8
	global_load_dword v111, v2, s[58:59] offset:12
	global_load_dword v112, v2, s[58:59] offset:16
	global_load_dword v113, v2, s[58:59] offset:20
	global_load_dword v114, v2, s[58:59] offset:24
	global_load_dword v115, v2, s[58:59] offset:28
	global_load_dwordx4 v[76:79], v0, s[100:101]
	s_add_u32 s100, s100, 0x8100
	s_addc_u32 s101, s101, 0
	global_load_dwordx4 v[80:83], v0, s[100:101]
	s_add_u32 s100, s100, 0x8100
	s_addc_u32 s101, s101, 0
	global_load_dwordx4 v[84:87], v0, s[100:101]
	s_add_u32 s100, s100, 0x8100
	s_addc_u32 s101, s101, 0
	global_load_dwordx4 v[88:91], v0, s[100:101]
	s_add_u32 s100, s100, 0x8100
	s_addc_u32 s101, s101, 0
	global_load_dwordx4 v[92:95], v0, s[100:101]
	s_add_u32 s100, s100, 0x8100
	s_addc_u32 s101, s101, 0
	global_load_dwordx4 v[96:99], v0, s[100:101]
	s_add_u32 s100, s100, 0x8100
	s_addc_u32 s101, s101, 0
	global_load_dwordx4 v[100:103], v0, s[100:101]
	s_add_u32 s100, s100, 0x8100
	s_addc_u32 s101, s101, 0
	global_load_dwordx4 v[104:107], v0, s[100:101]
	s_add_u32 s100, s100, 0x8100
	s_addc_u32 s101, s101, 0
	global_load_dword v116, v2, s[58:59] offset:32
	global_load_dword v117, v2, s[58:59] offset:36
	global_load_dword v118, v2, s[58:59] offset:40
	global_load_dword v119, v2, s[58:59] offset:44
	global_load_dword v120, v2, s[58:59] offset:48
	global_load_dword v121, v2, s[58:59] offset:52
	global_load_dword v122, v2, s[58:59] offset:56
	global_load_dword v123, v2, s[58:59] offset:60
	s_waitcnt vmcnt(16)
	v_cvt_pk_bf16_f32 v124, v8, v9
	v_cvt_pk_bf16_f32 v125, v10, v11
	v_cvt_pk_bf16_f32 v126, v12, v13
	v_cvt_pk_bf16_f32 v127, v14, v15
	v_mul_f32_e32 v128, 0x3fb8aa3b, v108
	v_exp_f32_e32 v128, v128
	global_store_dwordx4 v0, v[124:127], s[98:99]
	s_add_u32 s98, s98, 0x8100
	s_addc_u32 s99, s99, 0
	v_lshlrev_b32_e32 v130, 16, v44
	v_and_b32_e32 v131, 0xffff0000, v44
	v_lshlrev_b32_e32 v132, 16, v45
	v_and_b32_e32 v133, 0xffff0000, v45
	v_lshlrev_b32_e32 v134, 16, v46
	v_and_b32_e32 v135, 0xffff0000, v46
	v_lshlrev_b32_e32 v136, 16, v47
	v_and_b32_e32 v137, 0xffff0000, v47
	v_pk_fma_f32 v[8:9], v[8:9], v[128:129], v[130:131] op_sel_hi:[1,0,1]
	v_pk_fma_f32 v[10:11], v[10:11], v[128:129], v[132:133] op_sel_hi:[1,0,1]
	v_pk_fma_f32 v[12:13], v[12:13], v[128:129], v[134:135] op_sel_hi:[1,0,1]
	v_pk_fma_f32 v[14:15], v[14:15], v[128:129], v[136:137] op_sel_hi:[1,0,1]
	v_cvt_pk_bf16_f32 v124, v8, v9
	v_cvt_pk_bf16_f32 v125, v10, v11
	v_cvt_pk_bf16_f32 v126, v12, v13
	v_cvt_pk_bf16_f32 v127, v14, v15
	v_mul_f32_e32 v128, 0x3fb8aa3b, v109
	v_exp_f32_e32 v128, v128
	global_store_dwordx4 v0, v[124:127], s[98:99]
	s_add_u32 s98, s98, 0x8100
	s_addc_u32 s99, s99, 0
	v_lshlrev_b32_e32 v130, 16, v48
	v_and_b32_e32 v131, 0xffff0000, v48
	v_lshlrev_b32_e32 v132, 16, v49
	v_and_b32_e32 v133, 0xffff0000, v49
	v_lshlrev_b32_e32 v134, 16, v50
	v_and_b32_e32 v135, 0xffff0000, v50
	v_lshlrev_b32_e32 v136, 16, v51
	v_and_b32_e32 v137, 0xffff0000, v51
	v_pk_fma_f32 v[8:9], v[8:9], v[128:129], v[130:131] op_sel_hi:[1,0,1]
	v_pk_fma_f32 v[10:11], v[10:11], v[128:129], v[132:133] op_sel_hi:[1,0,1]
	v_pk_fma_f32 v[12:13], v[12:13], v[128:129], v[134:135] op_sel_hi:[1,0,1]
	v_pk_fma_f32 v[14:15], v[14:15], v[128:129], v[136:137] op_sel_hi:[1,0,1]
	v_cvt_pk_bf16_f32 v124, v8, v9
	v_cvt_pk_bf16_f32 v125, v10, v11
	v_cvt_pk_bf16_f32 v126, v12, v13
	v_cvt_pk_bf16_f32 v127, v14, v15
	v_mul_f32_e32 v128, 0x3fb8aa3b, v110
	v_exp_f32_e32 v128, v128
	global_store_dwordx4 v0, v[124:127], s[98:99]
	s_add_u32 s98, s98, 0x8100
	s_addc_u32 s99, s99, 0
	v_lshlrev_b32_e32 v130, 16, v52
	v_and_b32_e32 v131, 0xffff0000, v52
	v_lshlrev_b32_e32 v132, 16, v53
	v_and_b32_e32 v133, 0xffff0000, v53
	v_lshlrev_b32_e32 v134, 16, v54
	v_and_b32_e32 v135, 0xffff0000, v54
	v_lshlrev_b32_e32 v136, 16, v55
	v_and_b32_e32 v137, 0xffff0000, v55
	v_pk_fma_f32 v[8:9], v[8:9], v[128:129], v[130:131] op_sel_hi:[1,0,1]
	v_pk_fma_f32 v[10:11], v[10:11], v[128:129], v[132:133] op_sel_hi:[1,0,1]
	v_pk_fma_f32 v[12:13], v[12:13], v[128:129], v[134:135] op_sel_hi:[1,0,1]
	v_pk_fma_f32 v[14:15], v[14:15], v[128:129], v[136:137] op_sel_hi:[1,0,1]
	v_cvt_pk_bf16_f32 v124, v8, v9
	v_cvt_pk_bf16_f32 v125, v10, v11
	v_cvt_pk_bf16_f32 v126, v12, v13
	v_cvt_pk_bf16_f32 v127, v14, v15
	v_mul_f32_e32 v128, 0x3fb8aa3b, v111
	v_exp_f32_e32 v128, v128
	global_store_dwordx4 v0, v[124:127], s[98:99]
	s_add_u32 s98, s98, 0x8100
	s_addc_u32 s99, s99, 0
	v_lshlrev_b32_e32 v130, 16, v56
	v_and_b32_e32 v131, 0xffff0000, v56
	v_lshlrev_b32_e32 v132, 16, v57
	v_and_b32_e32 v133, 0xffff0000, v57
	v_lshlrev_b32_e32 v134, 16, v58
	v_and_b32_e32 v135, 0xffff0000, v58
	v_lshlrev_b32_e32 v136, 16, v59
	v_and_b32_e32 v137, 0xffff0000, v59
	v_pk_fma_f32 v[8:9], v[8:9], v[128:129], v[130:131] op_sel_hi:[1,0,1]
	v_pk_fma_f32 v[10:11], v[10:11], v[128:129], v[132:133] op_sel_hi:[1,0,1]
	v_pk_fma_f32 v[12:13], v[12:13], v[128:129], v[134:135] op_sel_hi:[1,0,1]
	v_pk_fma_f32 v[14:15], v[14:15], v[128:129], v[136:137] op_sel_hi:[1,0,1]
	v_cvt_pk_bf16_f32 v124, v8, v9
	v_cvt_pk_bf16_f32 v125, v10, v11
	v_cvt_pk_bf16_f32 v126, v12, v13
	v_cvt_pk_bf16_f32 v127, v14, v15
	v_mul_f32_e32 v128, 0x3fb8aa3b, v112
	v_exp_f32_e32 v128, v128
	global_store_dwordx4 v0, v[124:127], s[98:99]
	s_add_u32 s98, s98, 0x8100
	s_addc_u32 s99, s99, 0
	v_lshlrev_b32_e32 v130, 16, v60
	v_and_b32_e32 v131, 0xffff0000, v60
	v_lshlrev_b32_e32 v132, 16, v61
	v_and_b32_e32 v133, 0xffff0000, v61
	v_lshlrev_b32_e32 v134, 16, v62
	v_and_b32_e32 v135, 0xffff0000, v62
	v_lshlrev_b32_e32 v136, 16, v63
	v_and_b32_e32 v137, 0xffff0000, v63
	v_pk_fma_f32 v[8:9], v[8:9], v[128:129], v[130:131] op_sel_hi:[1,0,1]
	v_pk_fma_f32 v[10:11], v[10:11], v[128:129], v[132:133] op_sel_hi:[1,0,1]
	v_pk_fma_f32 v[12:13], v[12:13], v[128:129], v[134:135] op_sel_hi:[1,0,1]
	v_pk_fma_f32 v[14:15], v[14:15], v[128:129], v[136:137] op_sel_hi:[1,0,1]
	v_cvt_pk_bf16_f32 v124, v8, v9
	v_cvt_pk_bf16_f32 v125, v10, v11
	v_cvt_pk_bf16_f32 v126, v12, v13
	v_cvt_pk_bf16_f32 v127, v14, v15
	v_mul_f32_e32 v128, 0x3fb8aa3b, v113
	v_exp_f32_e32 v128, v128
	global_store_dwordx4 v0, v[124:127], s[98:99]
	s_add_u32 s98, s98, 0x8100
	s_addc_u32 s99, s99, 0
	v_lshlrev_b32_e32 v130, 16, v64
	v_and_b32_e32 v131, 0xffff0000, v64
	v_lshlrev_b32_e32 v132, 16, v65
	v_and_b32_e32 v133, 0xffff0000, v65
	v_lshlrev_b32_e32 v134, 16, v66
	v_and_b32_e32 v135, 0xffff0000, v66
	v_lshlrev_b32_e32 v136, 16, v67
	v_and_b32_e32 v137, 0xffff0000, v67
	v_pk_fma_f32 v[8:9], v[8:9], v[128:129], v[130:131] op_sel_hi:[1,0,1]
	v_pk_fma_f32 v[10:11], v[10:11], v[128:129], v[132:133] op_sel_hi:[1,0,1]
	v_pk_fma_f32 v[12:13], v[12:13], v[128:129], v[134:135] op_sel_hi:[1,0,1]
	v_pk_fma_f32 v[14:15], v[14:15], v[128:129], v[136:137] op_sel_hi:[1,0,1]
	v_cvt_pk_bf16_f32 v124, v8, v9
	v_cvt_pk_bf16_f32 v125, v10, v11
	v_cvt_pk_bf16_f32 v126, v12, v13
	v_cvt_pk_bf16_f32 v127, v14, v15
	v_mul_f32_e32 v128, 0x3fb8aa3b, v114
	v_exp_f32_e32 v128, v128
	global_store_dwordx4 v0, v[124:127], s[98:99]
	s_add_u32 s98, s98, 0x8100
	s_addc_u32 s99, s99, 0
	v_lshlrev_b32_e32 v130, 16, v68
	v_and_b32_e32 v131, 0xffff0000, v68
	v_lshlrev_b32_e32 v132, 16, v69
	v_and_b32_e32 v133, 0xffff0000, v69
	v_lshlrev_b32_e32 v134, 16, v70
	v_and_b32_e32 v135, 0xffff0000, v70
	v_lshlrev_b32_e32 v136, 16, v71
	v_and_b32_e32 v137, 0xffff0000, v71
	v_pk_fma_f32 v[8:9], v[8:9], v[128:129], v[130:131] op_sel_hi:[1,0,1]
	v_pk_fma_f32 v[10:11], v[10:11], v[128:129], v[132:133] op_sel_hi:[1,0,1]
	v_pk_fma_f32 v[12:13], v[12:13], v[128:129], v[134:135] op_sel_hi:[1,0,1]
	v_pk_fma_f32 v[14:15], v[14:15], v[128:129], v[136:137] op_sel_hi:[1,0,1]
	v_cvt_pk_bf16_f32 v124, v8, v9
	v_cvt_pk_bf16_f32 v125, v10, v11
	v_cvt_pk_bf16_f32 v126, v12, v13
	v_cvt_pk_bf16_f32 v127, v14, v15
	v_mul_f32_e32 v128, 0x3fb8aa3b, v115
	v_exp_f32_e32 v128, v128
	global_store_dwordx4 v0, v[124:127], s[98:99]
	s_add_u32 s98, s98, 0x8100
	s_addc_u32 s99, s99, 0
	v_lshlrev_b32_e32 v130, 16, v72
	v_and_b32_e32 v131, 0xffff0000, v72
	v_lshlrev_b32_e32 v132, 16, v73
	v_and_b32_e32 v133, 0xffff0000, v73
	v_lshlrev_b32_e32 v134, 16, v74
	v_and_b32_e32 v135, 0xffff0000, v74
	v_lshlrev_b32_e32 v136, 16, v75
	v_and_b32_e32 v137, 0xffff0000, v75
	v_pk_fma_f32 v[8:9], v[8:9], v[128:129], v[130:131] op_sel_hi:[1,0,1]
	v_pk_fma_f32 v[10:11], v[10:11], v[128:129], v[132:133] op_sel_hi:[1,0,1]
	v_pk_fma_f32 v[12:13], v[12:13], v[128:129], v[134:135] op_sel_hi:[1,0,1]
	v_pk_fma_f32 v[14:15], v[14:15], v[128:129], v[136:137] op_sel_hi:[1,0,1]
	global_load_dwordx4 v[44:47], v0, s[100:101]
	s_add_u32 s100, s100, 0x8100
	s_addc_u32 s101, s101, 0
	global_load_dwordx4 v[48:51], v0, s[100:101]
	s_add_u32 s100, s100, 0x8100
	s_addc_u32 s101, s101, 0
	global_load_dwordx4 v[52:55], v0, s[100:101]
	s_add_u32 s100, s100, 0x8100
	s_addc_u32 s101, s101, 0
	global_load_dwordx4 v[56:59], v0, s[100:101]
	s_add_u32 s100, s100, 0x8100
	s_addc_u32 s101, s101, 0
	global_load_dwordx4 v[60:63], v0, s[100:101]
	s_add_u32 s100, s100, 0x8100
	s_addc_u32 s101, s101, 0
	global_load_dwordx4 v[64:67], v0, s[100:101]
	s_add_u32 s100, s100, 0x8100
	s_addc_u32 s101, s101, 0
	global_load_dwordx4 v[68:71], v0, s[100:101]
	s_add_u32 s100, s100, 0x8100
	s_addc_u32 s101, s101, 0
	global_load_dwordx4 v[72:75], v0, s[100:101]
	s_add_u32 s100, s100, 0x8100
	s_addc_u32 s101, s101, 0
	global_load_dword v108, v2, s[58:59] offset:64
	global_load_dword v109, v2, s[58:59] offset:68
	global_load_dword v110, v2, s[58:59] offset:72
	global_load_dword v111, v2, s[58:59] offset:76
	global_load_dword v112, v2, s[58:59] offset:80
	global_load_dword v113, v2, s[58:59] offset:84
	global_load_dword v114, v2, s[58:59] offset:88
	global_load_dword v115, v2, s[58:59] offset:92
	s_waitcnt vmcnt(24)
	v_cvt_pk_bf16_f32 v124, v8, v9
	v_cvt_pk_bf16_f32 v125, v10, v11
	v_cvt_pk_bf16_f32 v126, v12, v13
	v_cvt_pk_bf16_f32 v127, v14, v15
	v_mul_f32_e32 v128, 0x3fb8aa3b, v116
	v_exp_f32_e32 v128, v128
	global_store_dwordx4 v0, v[124:127], s[98:99]
	s_add_u32 s98, s98, 0x8100
	s_addc_u32 s99, s99, 0
	v_lshlrev_b32_e32 v130, 16, v76
	v_and_b32_e32 v131, 0xffff0000, v76
	v_lshlrev_b32_e32 v132, 16, v77
	v_and_b32_e32 v133, 0xffff0000, v77
	v_lshlrev_b32_e32 v134, 16, v78
	v_and_b32_e32 v135, 0xffff0000, v78
	v_lshlrev_b32_e32 v136, 16, v79
	v_and_b32_e32 v137, 0xffff0000, v79
	v_pk_fma_f32 v[8:9], v[8:9], v[128:129], v[130:131] op_sel_hi:[1,0,1]
	v_pk_fma_f32 v[10:11], v[10:11], v[128:129], v[132:133] op_sel_hi:[1,0,1]
	v_pk_fma_f32 v[12:13], v[12:13], v[128:129], v[134:135] op_sel_hi:[1,0,1]
	v_pk_fma_f32 v[14:15], v[14:15], v[128:129], v[136:137] op_sel_hi:[1,0,1]
	v_cvt_pk_bf16_f32 v124, v8, v9
	v_cvt_pk_bf16_f32 v125, v10, v11
	v_cvt_pk_bf16_f32 v126, v12, v13
	v_cvt_pk_bf16_f32 v127, v14, v15
	v_mul_f32_e32 v128, 0x3fb8aa3b, v117
	v_exp_f32_e32 v128, v128
	global_store_dwordx4 v0, v[124:127], s[98:99]
	s_add_u32 s98, s98, 0x8100
	s_addc_u32 s99, s99, 0
	v_lshlrev_b32_e32 v130, 16, v80
	v_and_b32_e32 v131, 0xffff0000, v80
	v_lshlrev_b32_e32 v132, 16, v81
	v_and_b32_e32 v133, 0xffff0000, v81
	v_lshlrev_b32_e32 v134, 16, v82
	v_and_b32_e32 v135, 0xffff0000, v82
	v_lshlrev_b32_e32 v136, 16, v83
	v_and_b32_e32 v137, 0xffff0000, v83
	v_pk_fma_f32 v[8:9], v[8:9], v[128:129], v[130:131] op_sel_hi:[1,0,1]
	v_pk_fma_f32 v[10:11], v[10:11], v[128:129], v[132:133] op_sel_hi:[1,0,1]
	v_pk_fma_f32 v[12:13], v[12:13], v[128:129], v[134:135] op_sel_hi:[1,0,1]
	v_pk_fma_f32 v[14:15], v[14:15], v[128:129], v[136:137] op_sel_hi:[1,0,1]
	v_cvt_pk_bf16_f32 v124, v8, v9
	v_cvt_pk_bf16_f32 v125, v10, v11
	v_cvt_pk_bf16_f32 v126, v12, v13
	v_cvt_pk_bf16_f32 v127, v14, v15
	v_mul_f32_e32 v128, 0x3fb8aa3b, v118
	v_exp_f32_e32 v128, v128
	global_store_dwordx4 v0, v[124:127], s[98:99]
	s_add_u32 s98, s98, 0x8100
	s_addc_u32 s99, s99, 0
	v_lshlrev_b32_e32 v130, 16, v84
	v_and_b32_e32 v131, 0xffff0000, v84
	v_lshlrev_b32_e32 v132, 16, v85
	v_and_b32_e32 v133, 0xffff0000, v85
	v_lshlrev_b32_e32 v134, 16, v86
	v_and_b32_e32 v135, 0xffff0000, v86
	v_lshlrev_b32_e32 v136, 16, v87
	v_and_b32_e32 v137, 0xffff0000, v87
	v_pk_fma_f32 v[8:9], v[8:9], v[128:129], v[130:131] op_sel_hi:[1,0,1]
	v_pk_fma_f32 v[10:11], v[10:11], v[128:129], v[132:133] op_sel_hi:[1,0,1]
	v_pk_fma_f32 v[12:13], v[12:13], v[128:129], v[134:135] op_sel_hi:[1,0,1]
	v_pk_fma_f32 v[14:15], v[14:15], v[128:129], v[136:137] op_sel_hi:[1,0,1]
	v_cvt_pk_bf16_f32 v124, v8, v9
	v_cvt_pk_bf16_f32 v125, v10, v11
	v_cvt_pk_bf16_f32 v126, v12, v13
	v_cvt_pk_bf16_f32 v127, v14, v15
	v_mul_f32_e32 v128, 0x3fb8aa3b, v119
	v_exp_f32_e32 v128, v128
	global_store_dwordx4 v0, v[124:127], s[98:99]
	s_add_u32 s98, s98, 0x8100
	s_addc_u32 s99, s99, 0
	v_lshlrev_b32_e32 v130, 16, v88
	v_and_b32_e32 v131, 0xffff0000, v88
	v_lshlrev_b32_e32 v132, 16, v89
	v_and_b32_e32 v133, 0xffff0000, v89
	v_lshlrev_b32_e32 v134, 16, v90
	v_and_b32_e32 v135, 0xffff0000, v90
	v_lshlrev_b32_e32 v136, 16, v91
	v_and_b32_e32 v137, 0xffff0000, v91
	v_pk_fma_f32 v[8:9], v[8:9], v[128:129], v[130:131] op_sel_hi:[1,0,1]
	v_pk_fma_f32 v[10:11], v[10:11], v[128:129], v[132:133] op_sel_hi:[1,0,1]
	v_pk_fma_f32 v[12:13], v[12:13], v[128:129], v[134:135] op_sel_hi:[1,0,1]
	v_pk_fma_f32 v[14:15], v[14:15], v[128:129], v[136:137] op_sel_hi:[1,0,1]
	v_cvt_pk_bf16_f32 v124, v8, v9
	v_cvt_pk_bf16_f32 v125, v10, v11
	v_cvt_pk_bf16_f32 v126, v12, v13
	v_cvt_pk_bf16_f32 v127, v14, v15
	v_mul_f32_e32 v128, 0x3fb8aa3b, v120
	v_exp_f32_e32 v128, v128
	global_store_dwordx4 v0, v[124:127], s[98:99]
	s_add_u32 s98, s98, 0x8100
	s_addc_u32 s99, s99, 0
	v_lshlrev_b32_e32 v130, 16, v92
	v_and_b32_e32 v131, 0xffff0000, v92
	v_lshlrev_b32_e32 v132, 16, v93
	v_and_b32_e32 v133, 0xffff0000, v93
	v_lshlrev_b32_e32 v134, 16, v94
	v_and_b32_e32 v135, 0xffff0000, v94
	v_lshlrev_b32_e32 v136, 16, v95
	v_and_b32_e32 v137, 0xffff0000, v95
	v_pk_fma_f32 v[8:9], v[8:9], v[128:129], v[130:131] op_sel_hi:[1,0,1]
	v_pk_fma_f32 v[10:11], v[10:11], v[128:129], v[132:133] op_sel_hi:[1,0,1]
	v_pk_fma_f32 v[12:13], v[12:13], v[128:129], v[134:135] op_sel_hi:[1,0,1]
	v_pk_fma_f32 v[14:15], v[14:15], v[128:129], v[136:137] op_sel_hi:[1,0,1]
	v_cvt_pk_bf16_f32 v124, v8, v9
	v_cvt_pk_bf16_f32 v125, v10, v11
	v_cvt_pk_bf16_f32 v126, v12, v13
	v_cvt_pk_bf16_f32 v127, v14, v15
	v_mul_f32_e32 v128, 0x3fb8aa3b, v121
	v_exp_f32_e32 v128, v128
	global_store_dwordx4 v0, v[124:127], s[98:99]
	s_add_u32 s98, s98, 0x8100
	s_addc_u32 s99, s99, 0
	v_lshlrev_b32_e32 v130, 16, v96
	v_and_b32_e32 v131, 0xffff0000, v96
	v_lshlrev_b32_e32 v132, 16, v97
	v_and_b32_e32 v133, 0xffff0000, v97
	v_lshlrev_b32_e32 v134, 16, v98
	v_and_b32_e32 v135, 0xffff0000, v98
	v_lshlrev_b32_e32 v136, 16, v99
	v_and_b32_e32 v137, 0xffff0000, v99
	v_pk_fma_f32 v[8:9], v[8:9], v[128:129], v[130:131] op_sel_hi:[1,0,1]
	v_pk_fma_f32 v[10:11], v[10:11], v[128:129], v[132:133] op_sel_hi:[1,0,1]
	v_pk_fma_f32 v[12:13], v[12:13], v[128:129], v[134:135] op_sel_hi:[1,0,1]
	v_pk_fma_f32 v[14:15], v[14:15], v[128:129], v[136:137] op_sel_hi:[1,0,1]
	v_cvt_pk_bf16_f32 v124, v8, v9
	v_cvt_pk_bf16_f32 v125, v10, v11
	v_cvt_pk_bf16_f32 v126, v12, v13
	v_cvt_pk_bf16_f32 v127, v14, v15
	v_mul_f32_e32 v128, 0x3fb8aa3b, v122
	v_exp_f32_e32 v128, v128
	global_store_dwordx4 v0, v[124:127], s[98:99]
	s_add_u32 s98, s98, 0x8100
	s_addc_u32 s99, s99, 0
	v_lshlrev_b32_e32 v130, 16, v100
	v_and_b32_e32 v131, 0xffff0000, v100
	v_lshlrev_b32_e32 v132, 16, v101
	v_and_b32_e32 v133, 0xffff0000, v101
	v_lshlrev_b32_e32 v134, 16, v102
	v_and_b32_e32 v135, 0xffff0000, v102
	v_lshlrev_b32_e32 v136, 16, v103
	v_and_b32_e32 v137, 0xffff0000, v103
	v_pk_fma_f32 v[8:9], v[8:9], v[128:129], v[130:131] op_sel_hi:[1,0,1]
	v_pk_fma_f32 v[10:11], v[10:11], v[128:129], v[132:133] op_sel_hi:[1,0,1]
	v_pk_fma_f32 v[12:13], v[12:13], v[128:129], v[134:135] op_sel_hi:[1,0,1]
	v_pk_fma_f32 v[14:15], v[14:15], v[128:129], v[136:137] op_sel_hi:[1,0,1]
	v_cvt_pk_bf16_f32 v124, v8, v9
	v_cvt_pk_bf16_f32 v125, v10, v11
	v_cvt_pk_bf16_f32 v126, v12, v13
	v_cvt_pk_bf16_f32 v127, v14, v15
	v_mul_f32_e32 v128, 0x3fb8aa3b, v123
	v_exp_f32_e32 v128, v128
	global_store_dwordx4 v0, v[124:127], s[98:99]
	s_add_u32 s98, s98, 0x8100
	s_addc_u32 s99, s99, 0
	v_lshlrev_b32_e32 v130, 16, v104
	v_and_b32_e32 v131, 0xffff0000, v104
	v_lshlrev_b32_e32 v132, 16, v105
	v_and_b32_e32 v133, 0xffff0000, v105
	v_lshlrev_b32_e32 v134, 16, v106
	v_and_b32_e32 v135, 0xffff0000, v106
	v_lshlrev_b32_e32 v136, 16, v107
	v_and_b32_e32 v137, 0xffff0000, v107
	v_pk_fma_f32 v[8:9], v[8:9], v[128:129], v[130:131] op_sel_hi:[1,0,1]
	v_pk_fma_f32 v[10:11], v[10:11], v[128:129], v[132:133] op_sel_hi:[1,0,1]
	v_pk_fma_f32 v[12:13], v[12:13], v[128:129], v[134:135] op_sel_hi:[1,0,1]
	v_pk_fma_f32 v[14:15], v[14:15], v[128:129], v[136:137] op_sel_hi:[1,0,1]
	global_load_dwordx4 v[76:79], v0, s[100:101]
	s_add_u32 s100, s100, 0x8100
	s_addc_u32 s101, s101, 0
	global_load_dwordx4 v[80:83], v0, s[100:101]
	s_add_u32 s100, s100, 0x8100
	s_addc_u32 s101, s101, 0
	global_load_dwordx4 v[84:87], v0, s[100:101]
	s_add_u32 s100, s100, 0x8100
	s_addc_u32 s101, s101, 0
	global_load_dwordx4 v[88:91], v0, s[100:101]
	s_add_u32 s100, s100, 0x8100
	s_addc_u32 s101, s101, 0
	global_load_dwordx4 v[92:95], v0, s[100:101]
	s_add_u32 s100, s100, 0x8100
	s_addc_u32 s101, s101, 0
	global_load_dwordx4 v[96:99], v0, s[100:101]
	s_add_u32 s100, s100, 0x8100
	s_addc_u32 s101, s101, 0
	global_load_dwordx4 v[100:103], v0, s[100:101]
	s_add_u32 s100, s100, 0x8100
	s_addc_u32 s101, s101, 0
	global_load_dwordx4 v[104:107], v0, s[100:101]
	s_add_u32 s100, s100, 0x8100
	s_addc_u32 s101, s101, 0
	global_load_dword v116, v2, s[58:59] offset:96
	global_load_dword v117, v2, s[58:59] offset:100
	global_load_dword v118, v2, s[58:59] offset:104
	global_load_dword v119, v2, s[58:59] offset:108
	global_load_dword v120, v2, s[58:59] offset:112
	global_load_dword v121, v2, s[58:59] offset:116
	global_load_dword v122, v2, s[58:59] offset:120
	global_load_dword v123, v2, s[58:59] offset:124
	s_waitcnt vmcnt(24)
	v_cvt_pk_bf16_f32 v124, v8, v9
	v_cvt_pk_bf16_f32 v125, v10, v11
	v_cvt_pk_bf16_f32 v126, v12, v13
	v_cvt_pk_bf16_f32 v127, v14, v15
	v_mul_f32_e32 v128, 0x3fb8aa3b, v108
	v_exp_f32_e32 v128, v128
	global_store_dwordx4 v0, v[124:127], s[98:99]
	s_add_u32 s98, s98, 0x8100
	s_addc_u32 s99, s99, 0
	v_lshlrev_b32_e32 v130, 16, v44
	v_and_b32_e32 v131, 0xffff0000, v44
	v_lshlrev_b32_e32 v132, 16, v45
	v_and_b32_e32 v133, 0xffff0000, v45
	v_lshlrev_b32_e32 v134, 16, v46
	v_and_b32_e32 v135, 0xffff0000, v46
	v_lshlrev_b32_e32 v136, 16, v47
	v_and_b32_e32 v137, 0xffff0000, v47
	v_pk_fma_f32 v[8:9], v[8:9], v[128:129], v[130:131] op_sel_hi:[1,0,1]
	v_pk_fma_f32 v[10:11], v[10:11], v[128:129], v[132:133] op_sel_hi:[1,0,1]
	v_pk_fma_f32 v[12:13], v[12:13], v[128:129], v[134:135] op_sel_hi:[1,0,1]
	v_pk_fma_f32 v[14:15], v[14:15], v[128:129], v[136:137] op_sel_hi:[1,0,1]
	v_cvt_pk_bf16_f32 v124, v8, v9
	v_cvt_pk_bf16_f32 v125, v10, v11
	v_cvt_pk_bf16_f32 v126, v12, v13
	v_cvt_pk_bf16_f32 v127, v14, v15
	v_mul_f32_e32 v128, 0x3fb8aa3b, v109
	v_exp_f32_e32 v128, v128
	global_store_dwordx4 v0, v[124:127], s[98:99]
	s_add_u32 s98, s98, 0x8100
	s_addc_u32 s99, s99, 0
	v_lshlrev_b32_e32 v130, 16, v48
	v_and_b32_e32 v131, 0xffff0000, v48
	v_lshlrev_b32_e32 v132, 16, v49
	v_and_b32_e32 v133, 0xffff0000, v49
	v_lshlrev_b32_e32 v134, 16, v50
	v_and_b32_e32 v135, 0xffff0000, v50
	v_lshlrev_b32_e32 v136, 16, v51
	v_and_b32_e32 v137, 0xffff0000, v51
	v_pk_fma_f32 v[8:9], v[8:9], v[128:129], v[130:131] op_sel_hi:[1,0,1]
	v_pk_fma_f32 v[10:11], v[10:11], v[128:129], v[132:133] op_sel_hi:[1,0,1]
	v_pk_fma_f32 v[12:13], v[12:13], v[128:129], v[134:135] op_sel_hi:[1,0,1]
	v_pk_fma_f32 v[14:15], v[14:15], v[128:129], v[136:137] op_sel_hi:[1,0,1]
	v_cvt_pk_bf16_f32 v124, v8, v9
	v_cvt_pk_bf16_f32 v125, v10, v11
	v_cvt_pk_bf16_f32 v126, v12, v13
	v_cvt_pk_bf16_f32 v127, v14, v15
	v_mul_f32_e32 v128, 0x3fb8aa3b, v110
	v_exp_f32_e32 v128, v128
	global_store_dwordx4 v0, v[124:127], s[98:99]
	s_add_u32 s98, s98, 0x8100
	s_addc_u32 s99, s99, 0
	v_lshlrev_b32_e32 v130, 16, v52
	v_and_b32_e32 v131, 0xffff0000, v52
	v_lshlrev_b32_e32 v132, 16, v53
	v_and_b32_e32 v133, 0xffff0000, v53
	v_lshlrev_b32_e32 v134, 16, v54
	v_and_b32_e32 v135, 0xffff0000, v54
	v_lshlrev_b32_e32 v136, 16, v55
	v_and_b32_e32 v137, 0xffff0000, v55
	v_pk_fma_f32 v[8:9], v[8:9], v[128:129], v[130:131] op_sel_hi:[1,0,1]
	v_pk_fma_f32 v[10:11], v[10:11], v[128:129], v[132:133] op_sel_hi:[1,0,1]
	v_pk_fma_f32 v[12:13], v[12:13], v[128:129], v[134:135] op_sel_hi:[1,0,1]
	v_pk_fma_f32 v[14:15], v[14:15], v[128:129], v[136:137] op_sel_hi:[1,0,1]
	v_cvt_pk_bf16_f32 v124, v8, v9
	v_cvt_pk_bf16_f32 v125, v10, v11
	v_cvt_pk_bf16_f32 v126, v12, v13
	v_cvt_pk_bf16_f32 v127, v14, v15
	v_mul_f32_e32 v128, 0x3fb8aa3b, v111
	v_exp_f32_e32 v128, v128
	global_store_dwordx4 v0, v[124:127], s[98:99]
	s_add_u32 s98, s98, 0x8100
	s_addc_u32 s99, s99, 0
	v_lshlrev_b32_e32 v130, 16, v56
	v_and_b32_e32 v131, 0xffff0000, v56
	v_lshlrev_b32_e32 v132, 16, v57
	v_and_b32_e32 v133, 0xffff0000, v57
	v_lshlrev_b32_e32 v134, 16, v58
	v_and_b32_e32 v135, 0xffff0000, v58
	v_lshlrev_b32_e32 v136, 16, v59
	v_and_b32_e32 v137, 0xffff0000, v59
	v_pk_fma_f32 v[8:9], v[8:9], v[128:129], v[130:131] op_sel_hi:[1,0,1]
	v_pk_fma_f32 v[10:11], v[10:11], v[128:129], v[132:133] op_sel_hi:[1,0,1]
	v_pk_fma_f32 v[12:13], v[12:13], v[128:129], v[134:135] op_sel_hi:[1,0,1]
	v_pk_fma_f32 v[14:15], v[14:15], v[128:129], v[136:137] op_sel_hi:[1,0,1]
	v_cvt_pk_bf16_f32 v124, v8, v9
	v_cvt_pk_bf16_f32 v125, v10, v11
	v_cvt_pk_bf16_f32 v126, v12, v13
	v_cvt_pk_bf16_f32 v127, v14, v15
	v_mul_f32_e32 v128, 0x3fb8aa3b, v112
	v_exp_f32_e32 v128, v128
	global_store_dwordx4 v0, v[124:127], s[98:99]
	s_add_u32 s98, s98, 0x8100
	s_addc_u32 s99, s99, 0
	v_lshlrev_b32_e32 v130, 16, v60
	v_and_b32_e32 v131, 0xffff0000, v60
	v_lshlrev_b32_e32 v132, 16, v61
	v_and_b32_e32 v133, 0xffff0000, v61
	v_lshlrev_b32_e32 v134, 16, v62
	v_and_b32_e32 v135, 0xffff0000, v62
	v_lshlrev_b32_e32 v136, 16, v63
	v_and_b32_e32 v137, 0xffff0000, v63
	v_pk_fma_f32 v[8:9], v[8:9], v[128:129], v[130:131] op_sel_hi:[1,0,1]
	v_pk_fma_f32 v[10:11], v[10:11], v[128:129], v[132:133] op_sel_hi:[1,0,1]
	v_pk_fma_f32 v[12:13], v[12:13], v[128:129], v[134:135] op_sel_hi:[1,0,1]
	v_pk_fma_f32 v[14:15], v[14:15], v[128:129], v[136:137] op_sel_hi:[1,0,1]
	v_cvt_pk_bf16_f32 v124, v8, v9
	v_cvt_pk_bf16_f32 v125, v10, v11
	v_cvt_pk_bf16_f32 v126, v12, v13
	v_cvt_pk_bf16_f32 v127, v14, v15
	v_mul_f32_e32 v128, 0x3fb8aa3b, v113
	v_exp_f32_e32 v128, v128
	global_store_dwordx4 v0, v[124:127], s[98:99]
	s_add_u32 s98, s98, 0x8100
	s_addc_u32 s99, s99, 0
	v_lshlrev_b32_e32 v130, 16, v64
	v_and_b32_e32 v131, 0xffff0000, v64
	v_lshlrev_b32_e32 v132, 16, v65
	v_and_b32_e32 v133, 0xffff0000, v65
	v_lshlrev_b32_e32 v134, 16, v66
	v_and_b32_e32 v135, 0xffff0000, v66
	v_lshlrev_b32_e32 v136, 16, v67
	v_and_b32_e32 v137, 0xffff0000, v67
	v_pk_fma_f32 v[8:9], v[8:9], v[128:129], v[130:131] op_sel_hi:[1,0,1]
	v_pk_fma_f32 v[10:11], v[10:11], v[128:129], v[132:133] op_sel_hi:[1,0,1]
	v_pk_fma_f32 v[12:13], v[12:13], v[128:129], v[134:135] op_sel_hi:[1,0,1]
	v_pk_fma_f32 v[14:15], v[14:15], v[128:129], v[136:137] op_sel_hi:[1,0,1]
	v_cvt_pk_bf16_f32 v124, v8, v9
	v_cvt_pk_bf16_f32 v125, v10, v11
	v_cvt_pk_bf16_f32 v126, v12, v13
	v_cvt_pk_bf16_f32 v127, v14, v15
	v_mul_f32_e32 v128, 0x3fb8aa3b, v114
	v_exp_f32_e32 v128, v128
	global_store_dwordx4 v0, v[124:127], s[98:99]
	s_add_u32 s98, s98, 0x8100
	s_addc_u32 s99, s99, 0
	v_lshlrev_b32_e32 v130, 16, v68
	v_and_b32_e32 v131, 0xffff0000, v68
	v_lshlrev_b32_e32 v132, 16, v69
	v_and_b32_e32 v133, 0xffff0000, v69
	v_lshlrev_b32_e32 v134, 16, v70
	v_and_b32_e32 v135, 0xffff0000, v70
	v_lshlrev_b32_e32 v136, 16, v71
	v_and_b32_e32 v137, 0xffff0000, v71
	v_pk_fma_f32 v[8:9], v[8:9], v[128:129], v[130:131] op_sel_hi:[1,0,1]
	v_pk_fma_f32 v[10:11], v[10:11], v[128:129], v[132:133] op_sel_hi:[1,0,1]
	v_pk_fma_f32 v[12:13], v[12:13], v[128:129], v[134:135] op_sel_hi:[1,0,1]
	v_pk_fma_f32 v[14:15], v[14:15], v[128:129], v[136:137] op_sel_hi:[1,0,1]
	v_cvt_pk_bf16_f32 v124, v8, v9
	v_cvt_pk_bf16_f32 v125, v10, v11
	v_cvt_pk_bf16_f32 v126, v12, v13
	v_cvt_pk_bf16_f32 v127, v14, v15
	v_mul_f32_e32 v128, 0x3fb8aa3b, v115
	v_exp_f32_e32 v128, v128
	global_store_dwordx4 v0, v[124:127], s[98:99]
	s_add_u32 s98, s98, 0x8100
	s_addc_u32 s99, s99, 0
	v_lshlrev_b32_e32 v130, 16, v72
	v_and_b32_e32 v131, 0xffff0000, v72
	v_lshlrev_b32_e32 v132, 16, v73
	v_and_b32_e32 v133, 0xffff0000, v73
	v_lshlrev_b32_e32 v134, 16, v74
	v_and_b32_e32 v135, 0xffff0000, v74
	v_lshlrev_b32_e32 v136, 16, v75
	v_and_b32_e32 v137, 0xffff0000, v75
	v_pk_fma_f32 v[8:9], v[8:9], v[128:129], v[130:131] op_sel_hi:[1,0,1]
	v_pk_fma_f32 v[10:11], v[10:11], v[128:129], v[132:133] op_sel_hi:[1,0,1]
	v_pk_fma_f32 v[12:13], v[12:13], v[128:129], v[134:135] op_sel_hi:[1,0,1]
	v_pk_fma_f32 v[14:15], v[14:15], v[128:129], v[136:137] op_sel_hi:[1,0,1]
	global_load_dwordx4 v[44:47], v0, s[100:101]
	s_add_u32 s100, s100, 0x8100
	s_addc_u32 s101, s101, 0
	global_load_dwordx4 v[48:51], v0, s[100:101]
	s_add_u32 s100, s100, 0x8100
	s_addc_u32 s101, s101, 0
	global_load_dwordx4 v[52:55], v0, s[100:101]
	s_add_u32 s100, s100, 0x8100
	s_addc_u32 s101, s101, 0
	global_load_dwordx4 v[56:59], v0, s[100:101]
	s_add_u32 s100, s100, 0x8100
	s_addc_u32 s101, s101, 0
	global_load_dwordx4 v[60:63], v0, s[100:101]
	s_add_u32 s100, s100, 0x8100
	s_addc_u32 s101, s101, 0
	global_load_dwordx4 v[64:67], v0, s[100:101]
	s_add_u32 s100, s100, 0x8100
	s_addc_u32 s101, s101, 0
	global_load_dwordx4 v[68:71], v0, s[100:101]
	s_add_u32 s100, s100, 0x8100
	s_addc_u32 s101, s101, 0
	global_load_dwordx4 v[72:75], v0, s[100:101]
	s_add_u32 s100, s100, 0x8100
	s_addc_u32 s101, s101, 0
	global_load_dword v108, v2, s[58:59] offset:128
	global_load_dword v109, v2, s[58:59] offset:132
	global_load_dword v110, v2, s[58:59] offset:136
	global_load_dword v111, v2, s[58:59] offset:140
	global_load_dword v112, v2, s[58:59] offset:144
	global_load_dword v113, v2, s[58:59] offset:148
	global_load_dword v114, v2, s[58:59] offset:152
	global_load_dword v115, v2, s[58:59] offset:156
	s_waitcnt vmcnt(24)
	v_cvt_pk_bf16_f32 v124, v8, v9
	v_cvt_pk_bf16_f32 v125, v10, v11
	v_cvt_pk_bf16_f32 v126, v12, v13
	v_cvt_pk_bf16_f32 v127, v14, v15
	v_mul_f32_e32 v128, 0x3fb8aa3b, v116
	v_exp_f32_e32 v128, v128
	global_store_dwordx4 v0, v[124:127], s[98:99]
	s_add_u32 s98, s98, 0x8100
	s_addc_u32 s99, s99, 0
	v_lshlrev_b32_e32 v130, 16, v76
	v_and_b32_e32 v131, 0xffff0000, v76
	v_lshlrev_b32_e32 v132, 16, v77
	v_and_b32_e32 v133, 0xffff0000, v77
	v_lshlrev_b32_e32 v134, 16, v78
	v_and_b32_e32 v135, 0xffff0000, v78
	v_lshlrev_b32_e32 v136, 16, v79
	v_and_b32_e32 v137, 0xffff0000, v79
	v_pk_fma_f32 v[8:9], v[8:9], v[128:129], v[130:131] op_sel_hi:[1,0,1]
	v_pk_fma_f32 v[10:11], v[10:11], v[128:129], v[132:133] op_sel_hi:[1,0,1]
	v_pk_fma_f32 v[12:13], v[12:13], v[128:129], v[134:135] op_sel_hi:[1,0,1]
	v_pk_fma_f32 v[14:15], v[14:15], v[128:129], v[136:137] op_sel_hi:[1,0,1]
	v_cvt_pk_bf16_f32 v124, v8, v9
	v_cvt_pk_bf16_f32 v125, v10, v11
	v_cvt_pk_bf16_f32 v126, v12, v13
	v_cvt_pk_bf16_f32 v127, v14, v15
	v_mul_f32_e32 v128, 0x3fb8aa3b, v117
	v_exp_f32_e32 v128, v128
	global_store_dwordx4 v0, v[124:127], s[98:99]
	s_add_u32 s98, s98, 0x8100
	s_addc_u32 s99, s99, 0
	v_lshlrev_b32_e32 v130, 16, v80
	v_and_b32_e32 v131, 0xffff0000, v80
	v_lshlrev_b32_e32 v132, 16, v81
	v_and_b32_e32 v133, 0xffff0000, v81
	v_lshlrev_b32_e32 v134, 16, v82
	v_and_b32_e32 v135, 0xffff0000, v82
	v_lshlrev_b32_e32 v136, 16, v83
	v_and_b32_e32 v137, 0xffff0000, v83
	v_pk_fma_f32 v[8:9], v[8:9], v[128:129], v[130:131] op_sel_hi:[1,0,1]
	v_pk_fma_f32 v[10:11], v[10:11], v[128:129], v[132:133] op_sel_hi:[1,0,1]
	v_pk_fma_f32 v[12:13], v[12:13], v[128:129], v[134:135] op_sel_hi:[1,0,1]
	v_pk_fma_f32 v[14:15], v[14:15], v[128:129], v[136:137] op_sel_hi:[1,0,1]
	v_cvt_pk_bf16_f32 v124, v8, v9
	v_cvt_pk_bf16_f32 v125, v10, v11
	v_cvt_pk_bf16_f32 v126, v12, v13
	v_cvt_pk_bf16_f32 v127, v14, v15
	v_mul_f32_e32 v128, 0x3fb8aa3b, v118
	v_exp_f32_e32 v128, v128
	global_store_dwordx4 v0, v[124:127], s[98:99]
	s_add_u32 s98, s98, 0x8100
	s_addc_u32 s99, s99, 0
	v_lshlrev_b32_e32 v130, 16, v84
	v_and_b32_e32 v131, 0xffff0000, v84
	v_lshlrev_b32_e32 v132, 16, v85
	v_and_b32_e32 v133, 0xffff0000, v85
	v_lshlrev_b32_e32 v134, 16, v86
	v_and_b32_e32 v135, 0xffff0000, v86
	v_lshlrev_b32_e32 v136, 16, v87
	v_and_b32_e32 v137, 0xffff0000, v87
	v_pk_fma_f32 v[8:9], v[8:9], v[128:129], v[130:131] op_sel_hi:[1,0,1]
	v_pk_fma_f32 v[10:11], v[10:11], v[128:129], v[132:133] op_sel_hi:[1,0,1]
	v_pk_fma_f32 v[12:13], v[12:13], v[128:129], v[134:135] op_sel_hi:[1,0,1]
	v_pk_fma_f32 v[14:15], v[14:15], v[128:129], v[136:137] op_sel_hi:[1,0,1]
	v_cvt_pk_bf16_f32 v124, v8, v9
	v_cvt_pk_bf16_f32 v125, v10, v11
	v_cvt_pk_bf16_f32 v126, v12, v13
	v_cvt_pk_bf16_f32 v127, v14, v15
	v_mul_f32_e32 v128, 0x3fb8aa3b, v119
	v_exp_f32_e32 v128, v128
	global_store_dwordx4 v0, v[124:127], s[98:99]
	s_add_u32 s98, s98, 0x8100
	s_addc_u32 s99, s99, 0
	v_lshlrev_b32_e32 v130, 16, v88
	v_and_b32_e32 v131, 0xffff0000, v88
	v_lshlrev_b32_e32 v132, 16, v89
	v_and_b32_e32 v133, 0xffff0000, v89
	v_lshlrev_b32_e32 v134, 16, v90
	v_and_b32_e32 v135, 0xffff0000, v90
	v_lshlrev_b32_e32 v136, 16, v91
	v_and_b32_e32 v137, 0xffff0000, v91
	v_pk_fma_f32 v[8:9], v[8:9], v[128:129], v[130:131] op_sel_hi:[1,0,1]
	v_pk_fma_f32 v[10:11], v[10:11], v[128:129], v[132:133] op_sel_hi:[1,0,1]
	v_pk_fma_f32 v[12:13], v[12:13], v[128:129], v[134:135] op_sel_hi:[1,0,1]
	v_pk_fma_f32 v[14:15], v[14:15], v[128:129], v[136:137] op_sel_hi:[1,0,1]
	v_cvt_pk_bf16_f32 v124, v8, v9
	v_cvt_pk_bf16_f32 v125, v10, v11
	v_cvt_pk_bf16_f32 v126, v12, v13
	v_cvt_pk_bf16_f32 v127, v14, v15
	v_mul_f32_e32 v128, 0x3fb8aa3b, v120
	v_exp_f32_e32 v128, v128
	global_store_dwordx4 v0, v[124:127], s[98:99]
	s_add_u32 s98, s98, 0x8100
	s_addc_u32 s99, s99, 0
	v_lshlrev_b32_e32 v130, 16, v92
	v_and_b32_e32 v131, 0xffff0000, v92
	v_lshlrev_b32_e32 v132, 16, v93
	v_and_b32_e32 v133, 0xffff0000, v93
	v_lshlrev_b32_e32 v134, 16, v94
	v_and_b32_e32 v135, 0xffff0000, v94
	v_lshlrev_b32_e32 v136, 16, v95
	v_and_b32_e32 v137, 0xffff0000, v95
	v_pk_fma_f32 v[8:9], v[8:9], v[128:129], v[130:131] op_sel_hi:[1,0,1]
	v_pk_fma_f32 v[10:11], v[10:11], v[128:129], v[132:133] op_sel_hi:[1,0,1]
	v_pk_fma_f32 v[12:13], v[12:13], v[128:129], v[134:135] op_sel_hi:[1,0,1]
	v_pk_fma_f32 v[14:15], v[14:15], v[128:129], v[136:137] op_sel_hi:[1,0,1]
	v_cvt_pk_bf16_f32 v124, v8, v9
	v_cvt_pk_bf16_f32 v125, v10, v11
	v_cvt_pk_bf16_f32 v126, v12, v13
	v_cvt_pk_bf16_f32 v127, v14, v15
	v_mul_f32_e32 v128, 0x3fb8aa3b, v121
	v_exp_f32_e32 v128, v128
	global_store_dwordx4 v0, v[124:127], s[98:99]
	s_add_u32 s98, s98, 0x8100
	s_addc_u32 s99, s99, 0
	v_lshlrev_b32_e32 v130, 16, v96
	v_and_b32_e32 v131, 0xffff0000, v96
	v_lshlrev_b32_e32 v132, 16, v97
	v_and_b32_e32 v133, 0xffff0000, v97
	v_lshlrev_b32_e32 v134, 16, v98
	v_and_b32_e32 v135, 0xffff0000, v98
	v_lshlrev_b32_e32 v136, 16, v99
	v_and_b32_e32 v137, 0xffff0000, v99
	v_pk_fma_f32 v[8:9], v[8:9], v[128:129], v[130:131] op_sel_hi:[1,0,1]
	v_pk_fma_f32 v[10:11], v[10:11], v[128:129], v[132:133] op_sel_hi:[1,0,1]
	v_pk_fma_f32 v[12:13], v[12:13], v[128:129], v[134:135] op_sel_hi:[1,0,1]
	v_pk_fma_f32 v[14:15], v[14:15], v[128:129], v[136:137] op_sel_hi:[1,0,1]
	v_cvt_pk_bf16_f32 v124, v8, v9
	v_cvt_pk_bf16_f32 v125, v10, v11
	v_cvt_pk_bf16_f32 v126, v12, v13
	v_cvt_pk_bf16_f32 v127, v14, v15
	v_mul_f32_e32 v128, 0x3fb8aa3b, v122
	v_exp_f32_e32 v128, v128
	global_store_dwordx4 v0, v[124:127], s[98:99]
	s_add_u32 s98, s98, 0x8100
	s_addc_u32 s99, s99, 0
	v_lshlrev_b32_e32 v130, 16, v100
	v_and_b32_e32 v131, 0xffff0000, v100
	v_lshlrev_b32_e32 v132, 16, v101
	v_and_b32_e32 v133, 0xffff0000, v101
	v_lshlrev_b32_e32 v134, 16, v102
	v_and_b32_e32 v135, 0xffff0000, v102
	v_lshlrev_b32_e32 v136, 16, v103
	v_and_b32_e32 v137, 0xffff0000, v103
	v_pk_fma_f32 v[8:9], v[8:9], v[128:129], v[130:131] op_sel_hi:[1,0,1]
	v_pk_fma_f32 v[10:11], v[10:11], v[128:129], v[132:133] op_sel_hi:[1,0,1]
	v_pk_fma_f32 v[12:13], v[12:13], v[128:129], v[134:135] op_sel_hi:[1,0,1]
	v_pk_fma_f32 v[14:15], v[14:15], v[128:129], v[136:137] op_sel_hi:[1,0,1]
	v_cvt_pk_bf16_f32 v124, v8, v9
	v_cvt_pk_bf16_f32 v125, v10, v11
	v_cvt_pk_bf16_f32 v126, v12, v13
	v_cvt_pk_bf16_f32 v127, v14, v15
	v_mul_f32_e32 v128, 0x3fb8aa3b, v123
	v_exp_f32_e32 v128, v128
	global_store_dwordx4 v0, v[124:127], s[98:99]
	s_add_u32 s98, s98, 0x8100
	s_addc_u32 s99, s99, 0
	v_lshlrev_b32_e32 v130, 16, v104
	v_and_b32_e32 v131, 0xffff0000, v104
	v_lshlrev_b32_e32 v132, 16, v105
	v_and_b32_e32 v133, 0xffff0000, v105
	v_lshlrev_b32_e32 v134, 16, v106
	v_and_b32_e32 v135, 0xffff0000, v106
	v_lshlrev_b32_e32 v136, 16, v107
	v_and_b32_e32 v137, 0xffff0000, v107
	v_pk_fma_f32 v[8:9], v[8:9], v[128:129], v[130:131] op_sel_hi:[1,0,1]
	v_pk_fma_f32 v[10:11], v[10:11], v[128:129], v[132:133] op_sel_hi:[1,0,1]
	v_pk_fma_f32 v[12:13], v[12:13], v[128:129], v[134:135] op_sel_hi:[1,0,1]
	v_pk_fma_f32 v[14:15], v[14:15], v[128:129], v[136:137] op_sel_hi:[1,0,1]
	global_load_dwordx4 v[76:79], v0, s[100:101]
	s_add_u32 s100, s100, 0x8100
	s_addc_u32 s101, s101, 0
	global_load_dwordx4 v[80:83], v0, s[100:101]
	s_add_u32 s100, s100, 0x8100
	s_addc_u32 s101, s101, 0
	global_load_dwordx4 v[84:87], v0, s[100:101]
	s_add_u32 s100, s100, 0x8100
	s_addc_u32 s101, s101, 0
	global_load_dwordx4 v[88:91], v0, s[100:101]
	s_add_u32 s100, s100, 0x8100
	s_addc_u32 s101, s101, 0
	global_load_dwordx4 v[92:95], v0, s[100:101]
	s_add_u32 s100, s100, 0x8100
	s_addc_u32 s101, s101, 0
	global_load_dwordx4 v[96:99], v0, s[100:101]
	s_add_u32 s100, s100, 0x8100
	s_addc_u32 s101, s101, 0
	global_load_dwordx4 v[100:103], v0, s[100:101]
	s_add_u32 s100, s100, 0x8100
	s_addc_u32 s101, s101, 0
	global_load_dwordx4 v[104:107], v0, s[100:101]
	s_add_u32 s100, s100, 0x8100
	s_addc_u32 s101, s101, 0
	global_load_dword v116, v2, s[58:59] offset:160
	global_load_dword v117, v2, s[58:59] offset:164
	global_load_dword v118, v2, s[58:59] offset:168
	global_load_dword v119, v2, s[58:59] offset:172
	global_load_dword v120, v2, s[58:59] offset:176
	global_load_dword v121, v2, s[58:59] offset:180
	global_load_dword v122, v2, s[58:59] offset:184
	global_load_dword v123, v2, s[58:59] offset:188
	s_waitcnt vmcnt(24)
	v_cvt_pk_bf16_f32 v124, v8, v9
	v_cvt_pk_bf16_f32 v125, v10, v11
	v_cvt_pk_bf16_f32 v126, v12, v13
	v_cvt_pk_bf16_f32 v127, v14, v15
	v_mul_f32_e32 v128, 0x3fb8aa3b, v108
	v_exp_f32_e32 v128, v128
	global_store_dwordx4 v0, v[124:127], s[98:99]
	s_add_u32 s98, s98, 0x8100
	s_addc_u32 s99, s99, 0
	v_lshlrev_b32_e32 v130, 16, v44
	v_and_b32_e32 v131, 0xffff0000, v44
	v_lshlrev_b32_e32 v132, 16, v45
	v_and_b32_e32 v133, 0xffff0000, v45
	v_lshlrev_b32_e32 v134, 16, v46
	v_and_b32_e32 v135, 0xffff0000, v46
	v_lshlrev_b32_e32 v136, 16, v47
	v_and_b32_e32 v137, 0xffff0000, v47
	v_pk_fma_f32 v[8:9], v[8:9], v[128:129], v[130:131] op_sel_hi:[1,0,1]
	v_pk_fma_f32 v[10:11], v[10:11], v[128:129], v[132:133] op_sel_hi:[1,0,1]
	v_pk_fma_f32 v[12:13], v[12:13], v[128:129], v[134:135] op_sel_hi:[1,0,1]
	v_pk_fma_f32 v[14:15], v[14:15], v[128:129], v[136:137] op_sel_hi:[1,0,1]
	v_cvt_pk_bf16_f32 v124, v8, v9
	v_cvt_pk_bf16_f32 v125, v10, v11
	v_cvt_pk_bf16_f32 v126, v12, v13
	v_cvt_pk_bf16_f32 v127, v14, v15
	v_mul_f32_e32 v128, 0x3fb8aa3b, v109
	v_exp_f32_e32 v128, v128
	global_store_dwordx4 v0, v[124:127], s[98:99]
	s_add_u32 s98, s98, 0x8100
	s_addc_u32 s99, s99, 0
	v_lshlrev_b32_e32 v130, 16, v48
	v_and_b32_e32 v131, 0xffff0000, v48
	v_lshlrev_b32_e32 v132, 16, v49
	v_and_b32_e32 v133, 0xffff0000, v49
	v_lshlrev_b32_e32 v134, 16, v50
	v_and_b32_e32 v135, 0xffff0000, v50
	v_lshlrev_b32_e32 v136, 16, v51
	v_and_b32_e32 v137, 0xffff0000, v51
	v_pk_fma_f32 v[8:9], v[8:9], v[128:129], v[130:131] op_sel_hi:[1,0,1]
	v_pk_fma_f32 v[10:11], v[10:11], v[128:129], v[132:133] op_sel_hi:[1,0,1]
	v_pk_fma_f32 v[12:13], v[12:13], v[128:129], v[134:135] op_sel_hi:[1,0,1]
	v_pk_fma_f32 v[14:15], v[14:15], v[128:129], v[136:137] op_sel_hi:[1,0,1]
	v_cvt_pk_bf16_f32 v124, v8, v9
	v_cvt_pk_bf16_f32 v125, v10, v11
	v_cvt_pk_bf16_f32 v126, v12, v13
	v_cvt_pk_bf16_f32 v127, v14, v15
	v_mul_f32_e32 v128, 0x3fb8aa3b, v110
	v_exp_f32_e32 v128, v128
	global_store_dwordx4 v0, v[124:127], s[98:99]
	s_add_u32 s98, s98, 0x8100
	s_addc_u32 s99, s99, 0
	v_lshlrev_b32_e32 v130, 16, v52
	v_and_b32_e32 v131, 0xffff0000, v52
	v_lshlrev_b32_e32 v132, 16, v53
	v_and_b32_e32 v133, 0xffff0000, v53
	v_lshlrev_b32_e32 v134, 16, v54
	v_and_b32_e32 v135, 0xffff0000, v54
	v_lshlrev_b32_e32 v136, 16, v55
	v_and_b32_e32 v137, 0xffff0000, v55
	v_pk_fma_f32 v[8:9], v[8:9], v[128:129], v[130:131] op_sel_hi:[1,0,1]
	v_pk_fma_f32 v[10:11], v[10:11], v[128:129], v[132:133] op_sel_hi:[1,0,1]
	v_pk_fma_f32 v[12:13], v[12:13], v[128:129], v[134:135] op_sel_hi:[1,0,1]
	v_pk_fma_f32 v[14:15], v[14:15], v[128:129], v[136:137] op_sel_hi:[1,0,1]
	v_cvt_pk_bf16_f32 v124, v8, v9
	v_cvt_pk_bf16_f32 v125, v10, v11
	v_cvt_pk_bf16_f32 v126, v12, v13
	v_cvt_pk_bf16_f32 v127, v14, v15
	v_mul_f32_e32 v128, 0x3fb8aa3b, v111
	v_exp_f32_e32 v128, v128
	global_store_dwordx4 v0, v[124:127], s[98:99]
	s_add_u32 s98, s98, 0x8100
	s_addc_u32 s99, s99, 0
	v_lshlrev_b32_e32 v130, 16, v56
	v_and_b32_e32 v131, 0xffff0000, v56
	v_lshlrev_b32_e32 v132, 16, v57
	v_and_b32_e32 v133, 0xffff0000, v57
	v_lshlrev_b32_e32 v134, 16, v58
	v_and_b32_e32 v135, 0xffff0000, v58
	v_lshlrev_b32_e32 v136, 16, v59
	v_and_b32_e32 v137, 0xffff0000, v59
	v_pk_fma_f32 v[8:9], v[8:9], v[128:129], v[130:131] op_sel_hi:[1,0,1]
	v_pk_fma_f32 v[10:11], v[10:11], v[128:129], v[132:133] op_sel_hi:[1,0,1]
	v_pk_fma_f32 v[12:13], v[12:13], v[128:129], v[134:135] op_sel_hi:[1,0,1]
	v_pk_fma_f32 v[14:15], v[14:15], v[128:129], v[136:137] op_sel_hi:[1,0,1]
	v_cvt_pk_bf16_f32 v124, v8, v9
	v_cvt_pk_bf16_f32 v125, v10, v11
	v_cvt_pk_bf16_f32 v126, v12, v13
	v_cvt_pk_bf16_f32 v127, v14, v15
	v_mul_f32_e32 v128, 0x3fb8aa3b, v112
	v_exp_f32_e32 v128, v128
	global_store_dwordx4 v0, v[124:127], s[98:99]
	s_add_u32 s98, s98, 0x8100
	s_addc_u32 s99, s99, 0
	v_lshlrev_b32_e32 v130, 16, v60
	v_and_b32_e32 v131, 0xffff0000, v60
	v_lshlrev_b32_e32 v132, 16, v61
	v_and_b32_e32 v133, 0xffff0000, v61
	v_lshlrev_b32_e32 v134, 16, v62
	v_and_b32_e32 v135, 0xffff0000, v62
	v_lshlrev_b32_e32 v136, 16, v63
	v_and_b32_e32 v137, 0xffff0000, v63
	v_pk_fma_f32 v[8:9], v[8:9], v[128:129], v[130:131] op_sel_hi:[1,0,1]
	v_pk_fma_f32 v[10:11], v[10:11], v[128:129], v[132:133] op_sel_hi:[1,0,1]
	v_pk_fma_f32 v[12:13], v[12:13], v[128:129], v[134:135] op_sel_hi:[1,0,1]
	v_pk_fma_f32 v[14:15], v[14:15], v[128:129], v[136:137] op_sel_hi:[1,0,1]
	v_cvt_pk_bf16_f32 v124, v8, v9
	v_cvt_pk_bf16_f32 v125, v10, v11
	v_cvt_pk_bf16_f32 v126, v12, v13
	v_cvt_pk_bf16_f32 v127, v14, v15
	v_mul_f32_e32 v128, 0x3fb8aa3b, v113
	v_exp_f32_e32 v128, v128
	global_store_dwordx4 v0, v[124:127], s[98:99]
	s_add_u32 s98, s98, 0x8100
	s_addc_u32 s99, s99, 0
	v_lshlrev_b32_e32 v130, 16, v64
	v_and_b32_e32 v131, 0xffff0000, v64
	v_lshlrev_b32_e32 v132, 16, v65
	v_and_b32_e32 v133, 0xffff0000, v65
	v_lshlrev_b32_e32 v134, 16, v66
	v_and_b32_e32 v135, 0xffff0000, v66
	v_lshlrev_b32_e32 v136, 16, v67
	v_and_b32_e32 v137, 0xffff0000, v67
	v_pk_fma_f32 v[8:9], v[8:9], v[128:129], v[130:131] op_sel_hi:[1,0,1]
	v_pk_fma_f32 v[10:11], v[10:11], v[128:129], v[132:133] op_sel_hi:[1,0,1]
	v_pk_fma_f32 v[12:13], v[12:13], v[128:129], v[134:135] op_sel_hi:[1,0,1]
	v_pk_fma_f32 v[14:15], v[14:15], v[128:129], v[136:137] op_sel_hi:[1,0,1]
	v_cvt_pk_bf16_f32 v124, v8, v9
	v_cvt_pk_bf16_f32 v125, v10, v11
	v_cvt_pk_bf16_f32 v126, v12, v13
	v_cvt_pk_bf16_f32 v127, v14, v15
	v_mul_f32_e32 v128, 0x3fb8aa3b, v114
	v_exp_f32_e32 v128, v128
	global_store_dwordx4 v0, v[124:127], s[98:99]
	s_add_u32 s98, s98, 0x8100
	s_addc_u32 s99, s99, 0
	v_lshlrev_b32_e32 v130, 16, v68
	v_and_b32_e32 v131, 0xffff0000, v68
	v_lshlrev_b32_e32 v132, 16, v69
	v_and_b32_e32 v133, 0xffff0000, v69
	v_lshlrev_b32_e32 v134, 16, v70
	v_and_b32_e32 v135, 0xffff0000, v70
	v_lshlrev_b32_e32 v136, 16, v71
	v_and_b32_e32 v137, 0xffff0000, v71
	v_pk_fma_f32 v[8:9], v[8:9], v[128:129], v[130:131] op_sel_hi:[1,0,1]
	v_pk_fma_f32 v[10:11], v[10:11], v[128:129], v[132:133] op_sel_hi:[1,0,1]
	v_pk_fma_f32 v[12:13], v[12:13], v[128:129], v[134:135] op_sel_hi:[1,0,1]
	v_pk_fma_f32 v[14:15], v[14:15], v[128:129], v[136:137] op_sel_hi:[1,0,1]
	v_cvt_pk_bf16_f32 v124, v8, v9
	v_cvt_pk_bf16_f32 v125, v10, v11
	v_cvt_pk_bf16_f32 v126, v12, v13
	v_cvt_pk_bf16_f32 v127, v14, v15
	v_mul_f32_e32 v128, 0x3fb8aa3b, v115
	v_exp_f32_e32 v128, v128
	global_store_dwordx4 v0, v[124:127], s[98:99]
	s_add_u32 s98, s98, 0x8100
	s_addc_u32 s99, s99, 0
	v_lshlrev_b32_e32 v130, 16, v72
	v_and_b32_e32 v131, 0xffff0000, v72
	v_lshlrev_b32_e32 v132, 16, v73
	v_and_b32_e32 v133, 0xffff0000, v73
	v_lshlrev_b32_e32 v134, 16, v74
	v_and_b32_e32 v135, 0xffff0000, v74
	v_lshlrev_b32_e32 v136, 16, v75
	v_and_b32_e32 v137, 0xffff0000, v75
	v_pk_fma_f32 v[8:9], v[8:9], v[128:129], v[130:131] op_sel_hi:[1,0,1]
	v_pk_fma_f32 v[10:11], v[10:11], v[128:129], v[132:133] op_sel_hi:[1,0,1]
	v_pk_fma_f32 v[12:13], v[12:13], v[128:129], v[134:135] op_sel_hi:[1,0,1]
	v_pk_fma_f32 v[14:15], v[14:15], v[128:129], v[136:137] op_sel_hi:[1,0,1]
	global_load_dwordx4 v[44:47], v0, s[100:101]
	s_add_u32 s100, s100, 0x8100
	s_addc_u32 s101, s101, 0
	global_load_dwordx4 v[48:51], v0, s[100:101]
	s_add_u32 s100, s100, 0x8100
	s_addc_u32 s101, s101, 0
	global_load_dwordx4 v[52:55], v0, s[100:101]
	s_add_u32 s100, s100, 0x8100
	s_addc_u32 s101, s101, 0
	global_load_dwordx4 v[56:59], v0, s[100:101]
	s_add_u32 s100, s100, 0x8100
	s_addc_u32 s101, s101, 0
	global_load_dwordx4 v[60:63], v0, s[100:101]
	s_add_u32 s100, s100, 0x8100
	s_addc_u32 s101, s101, 0
	global_load_dwordx4 v[64:67], v0, s[100:101]
	s_add_u32 s100, s100, 0x8100
	s_addc_u32 s101, s101, 0
	global_load_dwordx4 v[68:71], v0, s[100:101]
	s_add_u32 s100, s100, 0x8100
	s_addc_u32 s101, s101, 0
	global_load_dwordx4 v[72:75], v0, s[100:101]
	s_add_u32 s100, s100, 0x8100
	s_addc_u32 s101, s101, 0
	global_load_dword v108, v2, s[58:59] offset:192
	global_load_dword v109, v2, s[58:59] offset:196
	global_load_dword v110, v2, s[58:59] offset:200
	global_load_dword v111, v2, s[58:59] offset:204
	global_load_dword v112, v2, s[58:59] offset:208
	global_load_dword v113, v2, s[58:59] offset:212
	global_load_dword v114, v2, s[58:59] offset:216
	global_load_dword v115, v2, s[58:59] offset:220
	s_waitcnt vmcnt(24)
	v_cvt_pk_bf16_f32 v124, v8, v9
	v_cvt_pk_bf16_f32 v125, v10, v11
	v_cvt_pk_bf16_f32 v126, v12, v13
	v_cvt_pk_bf16_f32 v127, v14, v15
	v_mul_f32_e32 v128, 0x3fb8aa3b, v116
	v_exp_f32_e32 v128, v128
	global_store_dwordx4 v0, v[124:127], s[98:99]
	s_add_u32 s98, s98, 0x8100
	s_addc_u32 s99, s99, 0
	v_lshlrev_b32_e32 v130, 16, v76
	v_and_b32_e32 v131, 0xffff0000, v76
	v_lshlrev_b32_e32 v132, 16, v77
	v_and_b32_e32 v133, 0xffff0000, v77
	v_lshlrev_b32_e32 v134, 16, v78
	v_and_b32_e32 v135, 0xffff0000, v78
	v_lshlrev_b32_e32 v136, 16, v79
	v_and_b32_e32 v137, 0xffff0000, v79
	v_pk_fma_f32 v[8:9], v[8:9], v[128:129], v[130:131] op_sel_hi:[1,0,1]
	v_pk_fma_f32 v[10:11], v[10:11], v[128:129], v[132:133] op_sel_hi:[1,0,1]
	v_pk_fma_f32 v[12:13], v[12:13], v[128:129], v[134:135] op_sel_hi:[1,0,1]
	v_pk_fma_f32 v[14:15], v[14:15], v[128:129], v[136:137] op_sel_hi:[1,0,1]
	v_cvt_pk_bf16_f32 v124, v8, v9
	v_cvt_pk_bf16_f32 v125, v10, v11
	v_cvt_pk_bf16_f32 v126, v12, v13
	v_cvt_pk_bf16_f32 v127, v14, v15
	v_mul_f32_e32 v128, 0x3fb8aa3b, v117
	v_exp_f32_e32 v128, v128
	global_store_dwordx4 v0, v[124:127], s[98:99]
	s_add_u32 s98, s98, 0x8100
	s_addc_u32 s99, s99, 0
	v_lshlrev_b32_e32 v130, 16, v80
	v_and_b32_e32 v131, 0xffff0000, v80
	v_lshlrev_b32_e32 v132, 16, v81
	v_and_b32_e32 v133, 0xffff0000, v81
	v_lshlrev_b32_e32 v134, 16, v82
	v_and_b32_e32 v135, 0xffff0000, v82
	v_lshlrev_b32_e32 v136, 16, v83
	v_and_b32_e32 v137, 0xffff0000, v83
	v_pk_fma_f32 v[8:9], v[8:9], v[128:129], v[130:131] op_sel_hi:[1,0,1]
	v_pk_fma_f32 v[10:11], v[10:11], v[128:129], v[132:133] op_sel_hi:[1,0,1]
	v_pk_fma_f32 v[12:13], v[12:13], v[128:129], v[134:135] op_sel_hi:[1,0,1]
	v_pk_fma_f32 v[14:15], v[14:15], v[128:129], v[136:137] op_sel_hi:[1,0,1]
	v_cvt_pk_bf16_f32 v124, v8, v9
	v_cvt_pk_bf16_f32 v125, v10, v11
	v_cvt_pk_bf16_f32 v126, v12, v13
	v_cvt_pk_bf16_f32 v127, v14, v15
	v_mul_f32_e32 v128, 0x3fb8aa3b, v118
	v_exp_f32_e32 v128, v128
	global_store_dwordx4 v0, v[124:127], s[98:99]
	s_add_u32 s98, s98, 0x8100
	s_addc_u32 s99, s99, 0
	v_lshlrev_b32_e32 v130, 16, v84
	v_and_b32_e32 v131, 0xffff0000, v84
	v_lshlrev_b32_e32 v132, 16, v85
	v_and_b32_e32 v133, 0xffff0000, v85
	v_lshlrev_b32_e32 v134, 16, v86
	v_and_b32_e32 v135, 0xffff0000, v86
	v_lshlrev_b32_e32 v136, 16, v87
	v_and_b32_e32 v137, 0xffff0000, v87
	v_pk_fma_f32 v[8:9], v[8:9], v[128:129], v[130:131] op_sel_hi:[1,0,1]
	v_pk_fma_f32 v[10:11], v[10:11], v[128:129], v[132:133] op_sel_hi:[1,0,1]
	v_pk_fma_f32 v[12:13], v[12:13], v[128:129], v[134:135] op_sel_hi:[1,0,1]
	v_pk_fma_f32 v[14:15], v[14:15], v[128:129], v[136:137] op_sel_hi:[1,0,1]
	v_cvt_pk_bf16_f32 v124, v8, v9
	v_cvt_pk_bf16_f32 v125, v10, v11
	v_cvt_pk_bf16_f32 v126, v12, v13
	v_cvt_pk_bf16_f32 v127, v14, v15
	v_mul_f32_e32 v128, 0x3fb8aa3b, v119
	v_exp_f32_e32 v128, v128
	global_store_dwordx4 v0, v[124:127], s[98:99]
	s_add_u32 s98, s98, 0x8100
	s_addc_u32 s99, s99, 0
	v_lshlrev_b32_e32 v130, 16, v88
	v_and_b32_e32 v131, 0xffff0000, v88
	v_lshlrev_b32_e32 v132, 16, v89
	v_and_b32_e32 v133, 0xffff0000, v89
	v_lshlrev_b32_e32 v134, 16, v90
	v_and_b32_e32 v135, 0xffff0000, v90
	v_lshlrev_b32_e32 v136, 16, v91
	v_and_b32_e32 v137, 0xffff0000, v91
	v_pk_fma_f32 v[8:9], v[8:9], v[128:129], v[130:131] op_sel_hi:[1,0,1]
	v_pk_fma_f32 v[10:11], v[10:11], v[128:129], v[132:133] op_sel_hi:[1,0,1]
	v_pk_fma_f32 v[12:13], v[12:13], v[128:129], v[134:135] op_sel_hi:[1,0,1]
	v_pk_fma_f32 v[14:15], v[14:15], v[128:129], v[136:137] op_sel_hi:[1,0,1]
	v_cvt_pk_bf16_f32 v124, v8, v9
	v_cvt_pk_bf16_f32 v125, v10, v11
	v_cvt_pk_bf16_f32 v126, v12, v13
	v_cvt_pk_bf16_f32 v127, v14, v15
	v_mul_f32_e32 v128, 0x3fb8aa3b, v120
	v_exp_f32_e32 v128, v128
	global_store_dwordx4 v0, v[124:127], s[98:99]
	s_add_u32 s98, s98, 0x8100
	s_addc_u32 s99, s99, 0
	v_lshlrev_b32_e32 v130, 16, v92
	v_and_b32_e32 v131, 0xffff0000, v92
	v_lshlrev_b32_e32 v132, 16, v93
	v_and_b32_e32 v133, 0xffff0000, v93
	v_lshlrev_b32_e32 v134, 16, v94
	v_and_b32_e32 v135, 0xffff0000, v94
	v_lshlrev_b32_e32 v136, 16, v95
	v_and_b32_e32 v137, 0xffff0000, v95
	v_pk_fma_f32 v[8:9], v[8:9], v[128:129], v[130:131] op_sel_hi:[1,0,1]
	v_pk_fma_f32 v[10:11], v[10:11], v[128:129], v[132:133] op_sel_hi:[1,0,1]
	v_pk_fma_f32 v[12:13], v[12:13], v[128:129], v[134:135] op_sel_hi:[1,0,1]
	v_pk_fma_f32 v[14:15], v[14:15], v[128:129], v[136:137] op_sel_hi:[1,0,1]
	v_cvt_pk_bf16_f32 v124, v8, v9
	v_cvt_pk_bf16_f32 v125, v10, v11
	v_cvt_pk_bf16_f32 v126, v12, v13
	v_cvt_pk_bf16_f32 v127, v14, v15
	v_mul_f32_e32 v128, 0x3fb8aa3b, v121
	v_exp_f32_e32 v128, v128
	global_store_dwordx4 v0, v[124:127], s[98:99]
	s_add_u32 s98, s98, 0x8100
	s_addc_u32 s99, s99, 0
	v_lshlrev_b32_e32 v130, 16, v96
	v_and_b32_e32 v131, 0xffff0000, v96
	v_lshlrev_b32_e32 v132, 16, v97
	v_and_b32_e32 v133, 0xffff0000, v97
	v_lshlrev_b32_e32 v134, 16, v98
	v_and_b32_e32 v135, 0xffff0000, v98
	v_lshlrev_b32_e32 v136, 16, v99
	v_and_b32_e32 v137, 0xffff0000, v99
	v_pk_fma_f32 v[8:9], v[8:9], v[128:129], v[130:131] op_sel_hi:[1,0,1]
	v_pk_fma_f32 v[10:11], v[10:11], v[128:129], v[132:133] op_sel_hi:[1,0,1]
	v_pk_fma_f32 v[12:13], v[12:13], v[128:129], v[134:135] op_sel_hi:[1,0,1]
	v_pk_fma_f32 v[14:15], v[14:15], v[128:129], v[136:137] op_sel_hi:[1,0,1]
	v_cvt_pk_bf16_f32 v124, v8, v9
	v_cvt_pk_bf16_f32 v125, v10, v11
	v_cvt_pk_bf16_f32 v126, v12, v13
	v_cvt_pk_bf16_f32 v127, v14, v15
	v_mul_f32_e32 v128, 0x3fb8aa3b, v122
	v_exp_f32_e32 v128, v128
	global_store_dwordx4 v0, v[124:127], s[98:99]
	s_add_u32 s98, s98, 0x8100
	s_addc_u32 s99, s99, 0
	v_lshlrev_b32_e32 v130, 16, v100
	v_and_b32_e32 v131, 0xffff0000, v100
	v_lshlrev_b32_e32 v132, 16, v101
	v_and_b32_e32 v133, 0xffff0000, v101
	v_lshlrev_b32_e32 v134, 16, v102
	v_and_b32_e32 v135, 0xffff0000, v102
	v_lshlrev_b32_e32 v136, 16, v103
	v_and_b32_e32 v137, 0xffff0000, v103
	v_pk_fma_f32 v[8:9], v[8:9], v[128:129], v[130:131] op_sel_hi:[1,0,1]
	v_pk_fma_f32 v[10:11], v[10:11], v[128:129], v[132:133] op_sel_hi:[1,0,1]
	v_pk_fma_f32 v[12:13], v[12:13], v[128:129], v[134:135] op_sel_hi:[1,0,1]
	v_pk_fma_f32 v[14:15], v[14:15], v[128:129], v[136:137] op_sel_hi:[1,0,1]
	v_cvt_pk_bf16_f32 v124, v8, v9
	v_cvt_pk_bf16_f32 v125, v10, v11
	v_cvt_pk_bf16_f32 v126, v12, v13
	v_cvt_pk_bf16_f32 v127, v14, v15
	v_mul_f32_e32 v128, 0x3fb8aa3b, v123
	v_exp_f32_e32 v128, v128
	global_store_dwordx4 v0, v[124:127], s[98:99]
	s_add_u32 s98, s98, 0x8100
	s_addc_u32 s99, s99, 0
	v_lshlrev_b32_e32 v130, 16, v104
	v_and_b32_e32 v131, 0xffff0000, v104
	v_lshlrev_b32_e32 v132, 16, v105
	v_and_b32_e32 v133, 0xffff0000, v105
	v_lshlrev_b32_e32 v134, 16, v106
	v_and_b32_e32 v135, 0xffff0000, v106
	v_lshlrev_b32_e32 v136, 16, v107
	v_and_b32_e32 v137, 0xffff0000, v107
	v_pk_fma_f32 v[8:9], v[8:9], v[128:129], v[130:131] op_sel_hi:[1,0,1]
	v_pk_fma_f32 v[10:11], v[10:11], v[128:129], v[132:133] op_sel_hi:[1,0,1]
	v_pk_fma_f32 v[12:13], v[12:13], v[128:129], v[134:135] op_sel_hi:[1,0,1]
	v_pk_fma_f32 v[14:15], v[14:15], v[128:129], v[136:137] op_sel_hi:[1,0,1]
	global_load_dwordx4 v[76:79], v0, s[100:101]
	s_add_u32 s100, s100, 0x8100
	s_addc_u32 s101, s101, 0
	global_load_dwordx4 v[80:83], v0, s[100:101]
	s_add_u32 s100, s100, 0x8100
	s_addc_u32 s101, s101, 0
	global_load_dwordx4 v[84:87], v0, s[100:101]
	s_add_u32 s100, s100, 0x8100
	s_addc_u32 s101, s101, 0
	global_load_dwordx4 v[88:91], v0, s[100:101]
	s_add_u32 s100, s100, 0x8100
	s_addc_u32 s101, s101, 0
	global_load_dwordx4 v[92:95], v0, s[100:101]
	s_add_u32 s100, s100, 0x8100
	s_addc_u32 s101, s101, 0
	global_load_dwordx4 v[96:99], v0, s[100:101]
	s_add_u32 s100, s100, 0x8100
	s_addc_u32 s101, s101, 0
	global_load_dwordx4 v[100:103], v0, s[100:101]
	s_add_u32 s100, s100, 0x8100
	s_addc_u32 s101, s101, 0
	global_load_dwordx4 v[104:107], v0, s[100:101]
	s_add_u32 s100, s100, 0x8100
	s_addc_u32 s101, s101, 0
	global_load_dword v116, v2, s[58:59] offset:224
	global_load_dword v117, v2, s[58:59] offset:228
	global_load_dword v118, v2, s[58:59] offset:232
	global_load_dword v119, v2, s[58:59] offset:236
	global_load_dword v120, v2, s[58:59] offset:240
	global_load_dword v121, v2, s[58:59] offset:244
	global_load_dword v122, v2, s[58:59] offset:248
	global_load_dword v123, v2, s[58:59] offset:252
	s_waitcnt vmcnt(24)
	v_cvt_pk_bf16_f32 v124, v8, v9
	v_cvt_pk_bf16_f32 v125, v10, v11
	v_cvt_pk_bf16_f32 v126, v12, v13
	v_cvt_pk_bf16_f32 v127, v14, v15
	v_mul_f32_e32 v128, 0x3fb8aa3b, v108
	v_exp_f32_e32 v128, v128
	global_store_dwordx4 v0, v[124:127], s[98:99]
	s_add_u32 s98, s98, 0x8100
	s_addc_u32 s99, s99, 0
	v_lshlrev_b32_e32 v130, 16, v44
	v_and_b32_e32 v131, 0xffff0000, v44
	v_lshlrev_b32_e32 v132, 16, v45
	v_and_b32_e32 v133, 0xffff0000, v45
	v_lshlrev_b32_e32 v134, 16, v46
	v_and_b32_e32 v135, 0xffff0000, v46
	v_lshlrev_b32_e32 v136, 16, v47
	v_and_b32_e32 v137, 0xffff0000, v47
	v_pk_fma_f32 v[8:9], v[8:9], v[128:129], v[130:131] op_sel_hi:[1,0,1]
	v_pk_fma_f32 v[10:11], v[10:11], v[128:129], v[132:133] op_sel_hi:[1,0,1]
	v_pk_fma_f32 v[12:13], v[12:13], v[128:129], v[134:135] op_sel_hi:[1,0,1]
	v_pk_fma_f32 v[14:15], v[14:15], v[128:129], v[136:137] op_sel_hi:[1,0,1]
	v_cvt_pk_bf16_f32 v124, v8, v9
	v_cvt_pk_bf16_f32 v125, v10, v11
	v_cvt_pk_bf16_f32 v126, v12, v13
	v_cvt_pk_bf16_f32 v127, v14, v15
	v_mul_f32_e32 v128, 0x3fb8aa3b, v109
	v_exp_f32_e32 v128, v128
	global_store_dwordx4 v0, v[124:127], s[98:99]
	s_add_u32 s98, s98, 0x8100
	s_addc_u32 s99, s99, 0
	v_lshlrev_b32_e32 v130, 16, v48
	v_and_b32_e32 v131, 0xffff0000, v48
	v_lshlrev_b32_e32 v132, 16, v49
	v_and_b32_e32 v133, 0xffff0000, v49
	v_lshlrev_b32_e32 v134, 16, v50
	v_and_b32_e32 v135, 0xffff0000, v50
	v_lshlrev_b32_e32 v136, 16, v51
	v_and_b32_e32 v137, 0xffff0000, v51
	v_pk_fma_f32 v[8:9], v[8:9], v[128:129], v[130:131] op_sel_hi:[1,0,1]
	v_pk_fma_f32 v[10:11], v[10:11], v[128:129], v[132:133] op_sel_hi:[1,0,1]
	v_pk_fma_f32 v[12:13], v[12:13], v[128:129], v[134:135] op_sel_hi:[1,0,1]
	v_pk_fma_f32 v[14:15], v[14:15], v[128:129], v[136:137] op_sel_hi:[1,0,1]
	v_cvt_pk_bf16_f32 v124, v8, v9
	v_cvt_pk_bf16_f32 v125, v10, v11
	v_cvt_pk_bf16_f32 v126, v12, v13
	v_cvt_pk_bf16_f32 v127, v14, v15
	v_mul_f32_e32 v128, 0x3fb8aa3b, v110
	v_exp_f32_e32 v128, v128
	global_store_dwordx4 v0, v[124:127], s[98:99]
	s_add_u32 s98, s98, 0x8100
	s_addc_u32 s99, s99, 0
	v_lshlrev_b32_e32 v130, 16, v52
	v_and_b32_e32 v131, 0xffff0000, v52
	v_lshlrev_b32_e32 v132, 16, v53
	v_and_b32_e32 v133, 0xffff0000, v53
	v_lshlrev_b32_e32 v134, 16, v54
	v_and_b32_e32 v135, 0xffff0000, v54
	v_lshlrev_b32_e32 v136, 16, v55
	v_and_b32_e32 v137, 0xffff0000, v55
	v_pk_fma_f32 v[8:9], v[8:9], v[128:129], v[130:131] op_sel_hi:[1,0,1]
	v_pk_fma_f32 v[10:11], v[10:11], v[128:129], v[132:133] op_sel_hi:[1,0,1]
	v_pk_fma_f32 v[12:13], v[12:13], v[128:129], v[134:135] op_sel_hi:[1,0,1]
	v_pk_fma_f32 v[14:15], v[14:15], v[128:129], v[136:137] op_sel_hi:[1,0,1]
	v_cvt_pk_bf16_f32 v124, v8, v9
	v_cvt_pk_bf16_f32 v125, v10, v11
	v_cvt_pk_bf16_f32 v126, v12, v13
	v_cvt_pk_bf16_f32 v127, v14, v15
	v_mul_f32_e32 v128, 0x3fb8aa3b, v111
	v_exp_f32_e32 v128, v128
	global_store_dwordx4 v0, v[124:127], s[98:99]
	s_add_u32 s98, s98, 0x8100
	s_addc_u32 s99, s99, 0
	v_lshlrev_b32_e32 v130, 16, v56
	v_and_b32_e32 v131, 0xffff0000, v56
	v_lshlrev_b32_e32 v132, 16, v57
	v_and_b32_e32 v133, 0xffff0000, v57
	v_lshlrev_b32_e32 v134, 16, v58
	v_and_b32_e32 v135, 0xffff0000, v58
	v_lshlrev_b32_e32 v136, 16, v59
	v_and_b32_e32 v137, 0xffff0000, v59
	v_pk_fma_f32 v[8:9], v[8:9], v[128:129], v[130:131] op_sel_hi:[1,0,1]
	v_pk_fma_f32 v[10:11], v[10:11], v[128:129], v[132:133] op_sel_hi:[1,0,1]
	v_pk_fma_f32 v[12:13], v[12:13], v[128:129], v[134:135] op_sel_hi:[1,0,1]
	v_pk_fma_f32 v[14:15], v[14:15], v[128:129], v[136:137] op_sel_hi:[1,0,1]
	v_cvt_pk_bf16_f32 v124, v8, v9
	v_cvt_pk_bf16_f32 v125, v10, v11
	v_cvt_pk_bf16_f32 v126, v12, v13
	v_cvt_pk_bf16_f32 v127, v14, v15
	v_mul_f32_e32 v128, 0x3fb8aa3b, v112
	v_exp_f32_e32 v128, v128
	global_store_dwordx4 v0, v[124:127], s[98:99]
	s_add_u32 s98, s98, 0x8100
	s_addc_u32 s99, s99, 0
	v_lshlrev_b32_e32 v130, 16, v60
	v_and_b32_e32 v131, 0xffff0000, v60
	v_lshlrev_b32_e32 v132, 16, v61
	v_and_b32_e32 v133, 0xffff0000, v61
	v_lshlrev_b32_e32 v134, 16, v62
	v_and_b32_e32 v135, 0xffff0000, v62
	v_lshlrev_b32_e32 v136, 16, v63
	v_and_b32_e32 v137, 0xffff0000, v63
	v_pk_fma_f32 v[8:9], v[8:9], v[128:129], v[130:131] op_sel_hi:[1,0,1]
	v_pk_fma_f32 v[10:11], v[10:11], v[128:129], v[132:133] op_sel_hi:[1,0,1]
	v_pk_fma_f32 v[12:13], v[12:13], v[128:129], v[134:135] op_sel_hi:[1,0,1]
	v_pk_fma_f32 v[14:15], v[14:15], v[128:129], v[136:137] op_sel_hi:[1,0,1]
	v_cvt_pk_bf16_f32 v124, v8, v9
	v_cvt_pk_bf16_f32 v125, v10, v11
	v_cvt_pk_bf16_f32 v126, v12, v13
	v_cvt_pk_bf16_f32 v127, v14, v15
	v_mul_f32_e32 v128, 0x3fb8aa3b, v113
	v_exp_f32_e32 v128, v128
	global_store_dwordx4 v0, v[124:127], s[98:99]
	s_add_u32 s98, s98, 0x8100
	s_addc_u32 s99, s99, 0
	v_lshlrev_b32_e32 v130, 16, v64
	v_and_b32_e32 v131, 0xffff0000, v64
	v_lshlrev_b32_e32 v132, 16, v65
	v_and_b32_e32 v133, 0xffff0000, v65
	v_lshlrev_b32_e32 v134, 16, v66
	v_and_b32_e32 v135, 0xffff0000, v66
	v_lshlrev_b32_e32 v136, 16, v67
	v_and_b32_e32 v137, 0xffff0000, v67
	v_pk_fma_f32 v[8:9], v[8:9], v[128:129], v[130:131] op_sel_hi:[1,0,1]
	v_pk_fma_f32 v[10:11], v[10:11], v[128:129], v[132:133] op_sel_hi:[1,0,1]
	v_pk_fma_f32 v[12:13], v[12:13], v[128:129], v[134:135] op_sel_hi:[1,0,1]
	v_pk_fma_f32 v[14:15], v[14:15], v[128:129], v[136:137] op_sel_hi:[1,0,1]
	v_cvt_pk_bf16_f32 v124, v8, v9
	v_cvt_pk_bf16_f32 v125, v10, v11
	v_cvt_pk_bf16_f32 v126, v12, v13
	v_cvt_pk_bf16_f32 v127, v14, v15
	v_mul_f32_e32 v128, 0x3fb8aa3b, v114
	v_exp_f32_e32 v128, v128
	global_store_dwordx4 v0, v[124:127], s[98:99]
	s_add_u32 s98, s98, 0x8100
	s_addc_u32 s99, s99, 0
	v_lshlrev_b32_e32 v130, 16, v68
	v_and_b32_e32 v131, 0xffff0000, v68
	v_lshlrev_b32_e32 v132, 16, v69
	v_and_b32_e32 v133, 0xffff0000, v69
	v_lshlrev_b32_e32 v134, 16, v70
	v_and_b32_e32 v135, 0xffff0000, v70
	v_lshlrev_b32_e32 v136, 16, v71
	v_and_b32_e32 v137, 0xffff0000, v71
	v_pk_fma_f32 v[8:9], v[8:9], v[128:129], v[130:131] op_sel_hi:[1,0,1]
	v_pk_fma_f32 v[10:11], v[10:11], v[128:129], v[132:133] op_sel_hi:[1,0,1]
	v_pk_fma_f32 v[12:13], v[12:13], v[128:129], v[134:135] op_sel_hi:[1,0,1]
	v_pk_fma_f32 v[14:15], v[14:15], v[128:129], v[136:137] op_sel_hi:[1,0,1]
	v_cvt_pk_bf16_f32 v124, v8, v9
	v_cvt_pk_bf16_f32 v125, v10, v11
	v_cvt_pk_bf16_f32 v126, v12, v13
	v_cvt_pk_bf16_f32 v127, v14, v15
	v_mul_f32_e32 v128, 0x3fb8aa3b, v115
	v_exp_f32_e32 v128, v128
	global_store_dwordx4 v0, v[124:127], s[98:99]
	s_add_u32 s98, s98, 0x8100
	s_addc_u32 s99, s99, 0
	v_lshlrev_b32_e32 v130, 16, v72
	v_and_b32_e32 v131, 0xffff0000, v72
	v_lshlrev_b32_e32 v132, 16, v73
	v_and_b32_e32 v133, 0xffff0000, v73
	v_lshlrev_b32_e32 v134, 16, v74
	v_and_b32_e32 v135, 0xffff0000, v74
	v_lshlrev_b32_e32 v136, 16, v75
	v_and_b32_e32 v137, 0xffff0000, v75
	v_pk_fma_f32 v[8:9], v[8:9], v[128:129], v[130:131] op_sel_hi:[1,0,1]
	v_pk_fma_f32 v[10:11], v[10:11], v[128:129], v[132:133] op_sel_hi:[1,0,1]
	v_pk_fma_f32 v[12:13], v[12:13], v[128:129], v[134:135] op_sel_hi:[1,0,1]
	v_pk_fma_f32 v[14:15], v[14:15], v[128:129], v[136:137] op_sel_hi:[1,0,1]
	s_waitcnt vmcnt(8)
	v_cvt_pk_bf16_f32 v124, v8, v9
	v_cvt_pk_bf16_f32 v125, v10, v11
	v_cvt_pk_bf16_f32 v126, v12, v13
	v_cvt_pk_bf16_f32 v127, v14, v15
	v_mul_f32_e32 v128, 0x3fb8aa3b, v116
	v_exp_f32_e32 v128, v128
	global_store_dwordx4 v0, v[124:127], s[98:99]
	s_add_u32 s98, s98, 0x8100
	s_addc_u32 s99, s99, 0
	v_lshlrev_b32_e32 v130, 16, v76
	v_and_b32_e32 v131, 0xffff0000, v76
	v_lshlrev_b32_e32 v132, 16, v77
	v_and_b32_e32 v133, 0xffff0000, v77
	v_lshlrev_b32_e32 v134, 16, v78
	v_and_b32_e32 v135, 0xffff0000, v78
	v_lshlrev_b32_e32 v136, 16, v79
	v_and_b32_e32 v137, 0xffff0000, v79
	v_pk_fma_f32 v[8:9], v[8:9], v[128:129], v[130:131] op_sel_hi:[1,0,1]
	v_pk_fma_f32 v[10:11], v[10:11], v[128:129], v[132:133] op_sel_hi:[1,0,1]
	v_pk_fma_f32 v[12:13], v[12:13], v[128:129], v[134:135] op_sel_hi:[1,0,1]
	v_pk_fma_f32 v[14:15], v[14:15], v[128:129], v[136:137] op_sel_hi:[1,0,1]
	v_cvt_pk_bf16_f32 v124, v8, v9
	v_cvt_pk_bf16_f32 v125, v10, v11
	v_cvt_pk_bf16_f32 v126, v12, v13
	v_cvt_pk_bf16_f32 v127, v14, v15
	v_mul_f32_e32 v128, 0x3fb8aa3b, v117
	v_exp_f32_e32 v128, v128
	global_store_dwordx4 v0, v[124:127], s[98:99]
	s_add_u32 s98, s98, 0x8100
	s_addc_u32 s99, s99, 0
	v_lshlrev_b32_e32 v130, 16, v80
	v_and_b32_e32 v131, 0xffff0000, v80
	v_lshlrev_b32_e32 v132, 16, v81
	v_and_b32_e32 v133, 0xffff0000, v81
	v_lshlrev_b32_e32 v134, 16, v82
	v_and_b32_e32 v135, 0xffff0000, v82
	v_lshlrev_b32_e32 v136, 16, v83
	v_and_b32_e32 v137, 0xffff0000, v83
	v_pk_fma_f32 v[8:9], v[8:9], v[128:129], v[130:131] op_sel_hi:[1,0,1]
	v_pk_fma_f32 v[10:11], v[10:11], v[128:129], v[132:133] op_sel_hi:[1,0,1]
	v_pk_fma_f32 v[12:13], v[12:13], v[128:129], v[134:135] op_sel_hi:[1,0,1]
	v_pk_fma_f32 v[14:15], v[14:15], v[128:129], v[136:137] op_sel_hi:[1,0,1]
	v_cvt_pk_bf16_f32 v124, v8, v9
	v_cvt_pk_bf16_f32 v125, v10, v11
	v_cvt_pk_bf16_f32 v126, v12, v13
	v_cvt_pk_bf16_f32 v127, v14, v15
	v_mul_f32_e32 v128, 0x3fb8aa3b, v118
	v_exp_f32_e32 v128, v128
	global_store_dwordx4 v0, v[124:127], s[98:99]
	s_add_u32 s98, s98, 0x8100
	s_addc_u32 s99, s99, 0
	v_lshlrev_b32_e32 v130, 16, v84
	v_and_b32_e32 v131, 0xffff0000, v84
	v_lshlrev_b32_e32 v132, 16, v85
	v_and_b32_e32 v133, 0xffff0000, v85
	v_lshlrev_b32_e32 v134, 16, v86
	v_and_b32_e32 v135, 0xffff0000, v86
	v_lshlrev_b32_e32 v136, 16, v87
	v_and_b32_e32 v137, 0xffff0000, v87
	v_pk_fma_f32 v[8:9], v[8:9], v[128:129], v[130:131] op_sel_hi:[1,0,1]
	v_pk_fma_f32 v[10:11], v[10:11], v[128:129], v[132:133] op_sel_hi:[1,0,1]
	v_pk_fma_f32 v[12:13], v[12:13], v[128:129], v[134:135] op_sel_hi:[1,0,1]
	v_pk_fma_f32 v[14:15], v[14:15], v[128:129], v[136:137] op_sel_hi:[1,0,1]
	v_cvt_pk_bf16_f32 v124, v8, v9
	v_cvt_pk_bf16_f32 v125, v10, v11
	v_cvt_pk_bf16_f32 v126, v12, v13
	v_cvt_pk_bf16_f32 v127, v14, v15
	v_mul_f32_e32 v128, 0x3fb8aa3b, v119
	v_exp_f32_e32 v128, v128
	global_store_dwordx4 v0, v[124:127], s[98:99]
	s_add_u32 s98, s98, 0x8100
	s_addc_u32 s99, s99, 0
	v_lshlrev_b32_e32 v130, 16, v88
	v_and_b32_e32 v131, 0xffff0000, v88
	v_lshlrev_b32_e32 v132, 16, v89
	v_and_b32_e32 v133, 0xffff0000, v89
	v_lshlrev_b32_e32 v134, 16, v90
	v_and_b32_e32 v135, 0xffff0000, v90
	v_lshlrev_b32_e32 v136, 16, v91
	v_and_b32_e32 v137, 0xffff0000, v91
	v_pk_fma_f32 v[8:9], v[8:9], v[128:129], v[130:131] op_sel_hi:[1,0,1]
	v_pk_fma_f32 v[10:11], v[10:11], v[128:129], v[132:133] op_sel_hi:[1,0,1]
	v_pk_fma_f32 v[12:13], v[12:13], v[128:129], v[134:135] op_sel_hi:[1,0,1]
	v_pk_fma_f32 v[14:15], v[14:15], v[128:129], v[136:137] op_sel_hi:[1,0,1]
	v_cvt_pk_bf16_f32 v124, v8, v9
	v_cvt_pk_bf16_f32 v125, v10, v11
	v_cvt_pk_bf16_f32 v126, v12, v13
	v_cvt_pk_bf16_f32 v127, v14, v15
	v_mul_f32_e32 v128, 0x3fb8aa3b, v120
	v_exp_f32_e32 v128, v128
	global_store_dwordx4 v0, v[124:127], s[98:99]
	s_add_u32 s98, s98, 0x8100
	s_addc_u32 s99, s99, 0
	v_lshlrev_b32_e32 v130, 16, v92
	v_and_b32_e32 v131, 0xffff0000, v92
	v_lshlrev_b32_e32 v132, 16, v93
	v_and_b32_e32 v133, 0xffff0000, v93
	v_lshlrev_b32_e32 v134, 16, v94
	v_and_b32_e32 v135, 0xffff0000, v94
	v_lshlrev_b32_e32 v136, 16, v95
	v_and_b32_e32 v137, 0xffff0000, v95
	v_pk_fma_f32 v[8:9], v[8:9], v[128:129], v[130:131] op_sel_hi:[1,0,1]
	v_pk_fma_f32 v[10:11], v[10:11], v[128:129], v[132:133] op_sel_hi:[1,0,1]
	v_pk_fma_f32 v[12:13], v[12:13], v[128:129], v[134:135] op_sel_hi:[1,0,1]
	v_pk_fma_f32 v[14:15], v[14:15], v[128:129], v[136:137] op_sel_hi:[1,0,1]
	v_cvt_pk_bf16_f32 v124, v8, v9
	v_cvt_pk_bf16_f32 v125, v10, v11
	v_cvt_pk_bf16_f32 v126, v12, v13
	v_cvt_pk_bf16_f32 v127, v14, v15
	v_mul_f32_e32 v128, 0x3fb8aa3b, v121
	v_exp_f32_e32 v128, v128
	global_store_dwordx4 v0, v[124:127], s[98:99]
	s_add_u32 s98, s98, 0x8100
	s_addc_u32 s99, s99, 0
	v_lshlrev_b32_e32 v130, 16, v96
	v_and_b32_e32 v131, 0xffff0000, v96
	v_lshlrev_b32_e32 v132, 16, v97
	v_and_b32_e32 v133, 0xffff0000, v97
	v_lshlrev_b32_e32 v134, 16, v98
	v_and_b32_e32 v135, 0xffff0000, v98
	v_lshlrev_b32_e32 v136, 16, v99
	v_and_b32_e32 v137, 0xffff0000, v99
	v_pk_fma_f32 v[8:9], v[8:9], v[128:129], v[130:131] op_sel_hi:[1,0,1]
	v_pk_fma_f32 v[10:11], v[10:11], v[128:129], v[132:133] op_sel_hi:[1,0,1]
	v_pk_fma_f32 v[12:13], v[12:13], v[128:129], v[134:135] op_sel_hi:[1,0,1]
	v_pk_fma_f32 v[14:15], v[14:15], v[128:129], v[136:137] op_sel_hi:[1,0,1]
	v_cvt_pk_bf16_f32 v124, v8, v9
	v_cvt_pk_bf16_f32 v125, v10, v11
	v_cvt_pk_bf16_f32 v126, v12, v13
	v_cvt_pk_bf16_f32 v127, v14, v15
	v_mul_f32_e32 v128, 0x3fb8aa3b, v122
	v_exp_f32_e32 v128, v128
	global_store_dwordx4 v0, v[124:127], s[98:99]
	s_add_u32 s98, s98, 0x8100
	s_addc_u32 s99, s99, 0
	v_lshlrev_b32_e32 v130, 16, v100
	v_and_b32_e32 v131, 0xffff0000, v100
	v_lshlrev_b32_e32 v132, 16, v101
	v_and_b32_e32 v133, 0xffff0000, v101
	v_lshlrev_b32_e32 v134, 16, v102
	v_and_b32_e32 v135, 0xffff0000, v102
	v_lshlrev_b32_e32 v136, 16, v103
	v_and_b32_e32 v137, 0xffff0000, v103
	v_pk_fma_f32 v[8:9], v[8:9], v[128:129], v[130:131] op_sel_hi:[1,0,1]
	v_pk_fma_f32 v[10:11], v[10:11], v[128:129], v[132:133] op_sel_hi:[1,0,1]
	v_pk_fma_f32 v[12:13], v[12:13], v[128:129], v[134:135] op_sel_hi:[1,0,1]
	v_pk_fma_f32 v[14:15], v[14:15], v[128:129], v[136:137] op_sel_hi:[1,0,1]
	v_cvt_pk_bf16_f32 v124, v8, v9
	v_cvt_pk_bf16_f32 v125, v10, v11
	v_cvt_pk_bf16_f32 v126, v12, v13
	v_cvt_pk_bf16_f32 v127, v14, v15
	v_mul_f32_e32 v128, 0x3fb8aa3b, v123
	v_exp_f32_e32 v128, v128
	global_store_dwordx4 v0, v[124:127], s[98:99]
	s_add_u32 s98, s98, 0x8100
	s_addc_u32 s99, s99, 0
	v_lshlrev_b32_e32 v130, 16, v104
	v_and_b32_e32 v131, 0xffff0000, v104
	v_lshlrev_b32_e32 v132, 16, v105
	v_and_b32_e32 v133, 0xffff0000, v105
	v_lshlrev_b32_e32 v134, 16, v106
	v_and_b32_e32 v135, 0xffff0000, v106
	v_lshlrev_b32_e32 v136, 16, v107
	v_and_b32_e32 v137, 0xffff0000, v107
	v_pk_fma_f32 v[8:9], v[8:9], v[128:129], v[130:131] op_sel_hi:[1,0,1]
	v_pk_fma_f32 v[10:11], v[10:11], v[128:129], v[132:133] op_sel_hi:[1,0,1]
	v_pk_fma_f32 v[12:13], v[12:13], v[128:129], v[134:135] op_sel_hi:[1,0,1]
	v_pk_fma_f32 v[14:15], v[14:15], v[128:129], v[136:137] op_sel_hi:[1,0,1]
	s_add_i32 s19, s19, s42
	s_cmpk_gt_i32 s19, 0x80
	s_cbranch_scc0 .LBB0_483
	s_setprio 0
	s_waitcnt vmcnt(0)
	s_barrier
	s_mov_b64 s[98:99], exec
	v_readlane_b32 s100, v255, 1
	v_readlane_b32 s101, v255, 2
	s_nop 1
	s_mov_b64 exec, s[100:101]
	s_cbranch_execz .Lscan_sig_skip
	buffer_wbl2 sc1
	s_waitcnt vmcnt(0)
	v_readlane_b32 s100, v255, 5
	v_readlane_b32 s101, v255, 6
	v_mov_b32_e32 v217, 0x300
	v_mov_b32_e32 v230, 1
	s_nop 4
	global_atomic_add v217, v230, s[100:101]
